# speedup vs baseline: 1.0081x; 1.0081x over previous
; #define SCHED __builtin_amdgcn_sched_barrier(0)
; template <int K, int EPI, bool MIX = false>
; __device__ __forceinline__ void gemm_phase(const Params& p, const u16* __restrict__ A, const u16* __restrict__ Bt,
;                            const float* __restrict__ rs_in, float* __restrict__ ssq_out, float alpha, bool rev = false) {
;     ...
;   for (;;) {
;     f32x4 acc[2][2][4][2];
; #pragma unroll
;     for (int a = 0; a < 2; ++a)
; #pragma unroll
;       for (int b = 0; b < 2; ++b)
; #pragma unroll
;         for (int m = 0; m < 4; ++m)
; #pragma unroll
;           for (int n = 0; n < 2; ++n) acc[a][b][m][n] = f32x4{0.f, 0.f, 0.f, 0.f};
;     bf16x8 At[4][2], B0[2][2], B1[2][2];
;     asm volatile("" ::: "memory");
;     SCHED;
.LBB0_87:
	s_andn2_b64 vcc, exec, s[38:39]
	s_cbranch_vccz .LBB0_112
	s_and_b64 vcc, exec, s[18:19]
	s_cbranch_vccnz .Llate_p1_done
	s_barrier
.Llate_p1_done:
.LBB0_88:
	s_mov_b32 s80, s40
	v_mov_b32_e32 v0, 0
	s_mov_b32 s81, -2
	s_mov_b64 s[4:5], s[8:9]
	s_mov_b64 s[38:39], s[0:1]
	s_mov_b64 s[40:41], s[6:7]
	v_mov_b32_e32 v1, v0
	v_mov_b32_e32 v2, v0
	v_mov_b32_e32 v3, v0
	v_mov_b32_e32 v4, v0
	v_mov_b32_e32 v5, v0
	v_mov_b32_e32 v6, v0
	v_mov_b32_e32 v7, v0
	v_mov_b32_e32 v8, v0
	v_mov_b32_e32 v9, v0
	v_mov_b32_e32 v10, v0
	v_mov_b32_e32 v11, v0
	v_mov_b32_e32 v12, v0
	v_mov_b32_e32 v13, v0
	v_mov_b32_e32 v14, v0
	v_mov_b32_e32 v15, v0
	v_mov_b32_e32 v16, v0
	v_mov_b32_e32 v17, v0
	v_mov_b32_e32 v18, v0
	v_mov_b32_e32 v19, v0
	v_mov_b32_e32 v20, v0
	v_mov_b32_e32 v21, v0
	v_mov_b32_e32 v22, v0
	v_mov_b32_e32 v23, v0
	v_mov_b32_e32 v24, v0
	v_mov_b32_e32 v25, v0
	v_mov_b32_e32 v26, v0
	v_mov_b32_e32 v27, v0
	v_mov_b32_e32 v28, v0
	v_mov_b32_e32 v29, v0
	v_mov_b32_e32 v30, v0
	v_mov_b32_e32 v31, v0
	v_mov_b32_e32 v56, v0
	v_mov_b32_e32 v57, v0
	v_mov_b32_e32 v58, v0
	v_mov_b32_e32 v59, v0
	v_mov_b32_e32 v68, v0
	v_mov_b32_e32 v69, v0
	v_mov_b32_e32 v70, v0
	v_mov_b32_e32 v71, v0
	v_mov_b32_e32 v72, v0
	v_mov_b32_e32 v73, v0
	v_mov_b32_e32 v74, v0
	v_mov_b32_e32 v75, v0
	v_mov_b32_e32 v76, v0
	v_mov_b32_e32 v77, v0
	v_mov_b32_e32 v78, v0
	v_mov_b32_e32 v79, v0
	v_mov_b32_e32 v80, v0
	v_mov_b32_e32 v81, v0
	v_mov_b32_e32 v82, v0
	v_mov_b32_e32 v83, v0
	v_mov_b32_e32 v84, v0
	v_mov_b32_e32 v85, v0
	v_mov_b32_e32 v86, v0
	v_mov_b32_e32 v87, v0
	v_mov_b32_e32 v88, v0
	v_mov_b32_e32 v89, v0
	v_mov_b32_e32 v90, v0
	v_mov_b32_e32 v91, v0
	v_mov_b32_e32 v92, v0
	v_mov_b32_e32 v93, v0
	v_mov_b32_e32 v94, v0
	v_mov_b32_e32 v95, v0
	v_mov_b32_e32 v96, v0
	v_mov_b32_e32 v97, v0
	v_mov_b32_e32 v98, v0
	v_mov_b32_e32 v99, v0
	v_mov_b32_e32 v100, v0
	v_mov_b32_e32 v101, v0
	v_mov_b32_e32 v102, v0
	v_mov_b32_e32 v103, v0
	v_mov_b32_e32 v104, v0
	v_mov_b32_e32 v105, v0
	v_mov_b32_e32 v106, v0
	v_mov_b32_e32 v107, v0
	v_mov_b32_e32 v108, v0
	v_mov_b32_e32 v109, v0
	v_mov_b32_e32 v110, v0
	v_mov_b32_e32 v111, v0
	v_mov_b32_e32 v112, v0
	v_mov_b32_e32 v113, v0
	v_mov_b32_e32 v114, v0
	v_mov_b32_e32 v115, v0
	v_mov_b32_e32 v116, v0
	v_mov_b32_e32 v117, v0
	v_mov_b32_e32 v118, v0
	v_mov_b32_e32 v119, v0
	v_mov_b32_e32 v120, v0
	v_mov_b32_e32 v121, v0
	v_mov_b32_e32 v122, v0
	v_mov_b32_e32 v123, v0
	v_mov_b32_e32 v124, v0
	v_mov_b32_e32 v125, v0
	v_mov_b32_e32 v126, v0
	v_mov_b32_e32 v127, v0
	v_mov_b32_e32 v32, v0
	v_mov_b32_e32 v33, v0
	v_mov_b32_e32 v34, v0
	v_mov_b32_e32 v35, v0
	v_mov_b32_e32 v36, v0
	v_mov_b32_e32 v37, v0
	v_mov_b32_e32 v38, v0
	v_mov_b32_e32 v39, v0
	v_mov_b32_e32 v40, v0
	v_mov_b32_e32 v41, v0
	v_mov_b32_e32 v42, v0
	v_mov_b32_e32 v43, v0
	v_mov_b32_e32 v44, v0
	v_mov_b32_e32 v45, v0
	v_mov_b32_e32 v46, v0
	v_mov_b32_e32 v47, v0
	v_mov_b32_e32 v48, v0
	v_mov_b32_e32 v49, v0
	v_mov_b32_e32 v50, v0
	v_mov_b32_e32 v51, v0
	v_mov_b32_e32 v52, v0
	v_mov_b32_e32 v53, v0
	v_mov_b32_e32 v54, v0
	v_mov_b32_e32 v55, v0
	v_mov_b32_e32 v60, v0
	v_mov_b32_e32 v61, v0
	v_mov_b32_e32 v62, v0
	v_mov_b32_e32 v63, v0
	v_mov_b32_e32 v64, v0
	v_mov_b32_e32 v65, v0
	v_mov_b32_e32 v66, v0
	v_mov_b32_e32 v67, v0

; #define MMA(ai,bj,Af,Bf) do{__builtin_amdgcn_s_setprio(1); \
;     _Pragma("unroll") for(int m=0;m<4;++m) _Pragma("unroll") for(int n=0;n<2;++n) _Pragma("unroll") for(int k=0;k<2;++k) \
;       acc[ai][bj][m][n]=__builtin_amdgcn_mfma_f32_16x16x32_bf16(Bf[n][k],Af[m][k],acc[ai][bj][m][n],0,0,0); \
;     __builtin_amdgcn_s_setprio(0);}while(0)
; #define WAIT_V(n) asm volatile("s_waitcnt vmcnt(" #n ")":::"memory")
; #define BAR __builtin_amdgcn_s_barrier()
; #define STAGE_B(b,h,kt) do{ unsigned char* _d = SB(b,h) + wbase; \
;     if constexpr (BLK) { const char* _s = ((h)?baseB1:baseB0) + (size_t)(kt) * 16384; GLDS(_s + voa, _d); GLDS(_s + 8192 + voa, _d + 8192); } \
;     else { const char* _s = ((h)?baseB1:baseB0) + (kt)*128; GLDS(_s + voa, _d); GLDS(_s + (size_t)128*K + voa, _d + 8192); } }while(0)
; template <int K, int EPI, bool MIX = false>
; __device__ __forceinline__ void gemm_phase(const Params& p, const u16* __restrict__ A, const u16* __restrict__ Bt,
;                            const float* __restrict__ rs_in, float* __restrict__ ssq_out, float alpha, bool rev = false) {
;     ...
;       if (more) { STAGE_B(1,1,1); WAIT_V(6); }
;       BAR; MMA(1,1,At,B1); BAR;
;       if (!more && wr == 0) BAR;
;     ...
;     if constexpr (EPI == EPI_SWIGLU) {
; #pragma unroll
;       for (int ai = 0; ai < 2; ++ai)
; #pragma unroll
;         for (int m = 0; m < 4; ++m) {
;           int row = brow + ai * 128 + wr * 64 + m * 16 + fr_e;
;           const float rs = rsqrtf(rsq[ai][m] * (1.f / DM) + 1e-6f);
;           const float c1 = rs * -1.4426950408889634f, rs2 = rs * rs;
;           u16* orow = p.Bbuf + blk_off(row, cpn * 128 + wc * 32, DFF) + wn16;
;           uint2 o2[2];
; #pragma unroll
;           for (int n = 0; n < 2; ++n) {
;             f32x4 g = acc[ai][0][m][n], u = acc[ai][1][m][n];
;             float h[4];
; #pragma unroll
;             for (int j = 0; j < 4; ++j) h[j] = (g[j] * u[j]) * (rs2 * __builtin_amdgcn_rcpf(1.f + __builtin_amdgcn_exp2f(g[j] * c1)));
;             o2[n].x = pk2(h[0], h[1]); o2[n].y = pk2(h[2], h[3]);
;           }
;           *(uint4*)orow = widen_pair(o2[0], o2[1]);
;         }
.LBB0_108:
	s_barrier
	s_setprio 1
	v_mfma_f32_16x16x32_bf16 v[4:7], v[128:131], v[200:203], v[144:147]
	v_mfma_f32_16x16x32_bf16 v[60:63], v[140:143], v[204:207], v[4:7]
	v_mfma_f32_16x16x32_bf16 v[4:7], v[132:135], v[200:203], v[36:39]
	v_mfma_f32_16x16x32_bf16 v[52:55], v[136:139], v[204:207], v[4:7]
	v_mfma_f32_16x16x32_bf16 v[4:7], v[128:131], v[188:191], v[148:151]
	v_mfma_f32_16x16x32_bf16 v[44:47], v[140:143], v[192:195], v[4:7]
	v_mfma_f32_16x16x32_bf16 v[4:7], v[132:135], v[188:191], v[152:155]
	v_mfma_f32_16x16x32_bf16 v[36:39], v[136:139], v[192:195], v[4:7]
	v_mfma_f32_16x16x32_bf16 v[4:7], v[128:131], v[168:171], v[156:159]
	v_mfma_f32_16x16x32_bf16 v[28:31], v[140:143], v[196:199], v[4:7]
	v_mfma_f32_16x16x32_bf16 v[4:7], v[132:135], v[168:171], v[172:175]
	v_mfma_f32_16x16x32_bf16 v[20:23], v[136:139], v[196:199], v[4:7]
	v_mfma_f32_16x16x32_bf16 v[4:7], v[128:131], v[160:163], v[176:179]
	v_mfma_f32_16x16x32_bf16 v[12:15], v[140:143], v[164:167], v[4:7]
	v_mfma_f32_16x16x32_bf16 v[4:7], v[132:135], v[160:163], v[180:183]
	v_mfma_f32_16x16x32_bf16 v[4:7], v[136:139], v[164:167], v[4:7]
	s_setprio 0
	s_or_b64 vcc, s[4:5], s[18:19]
	s_cbranch_scc0 .Llate_p1_defer
	s_barrier
.Llate_p1_defer:
	s_andn2_b64 vcc, exec, s[38:39]
	s_cbranch_vccnz .LBB0_110
	s_barrier
.LBB0_110:
	v_mov_b32_e32 v129, v220
	v_pk_mul_f32 v[126:127], v[122:123], v[126:127]
	v_lshrrev_b32_e32 v130, 1, v129
	v_ashrrev_i32_e32 v128, 1, v129
	v_and_b32_e32 v130, 8, v130
	v_and_or_b32 v128, v128, -16, v130
	s_waitcnt vmcnt(6)
	v_fmamk_f32 v130, v210, 0x3a000000, v234
	v_cmp_gt_f32_e32 vcc, s78, v130
	v_mul_f32_e32 v132, 0x4b800000, v130
	v_and_or_b32 v131, v129, 15, s50
	v_cndmask_b32_e32 v130, v130, v132, vcc
	v_rsq_f32_e32 v130, v130
	v_lshlrev_b32_e32 v131, 7, v131
	v_and_b32_e32 v210, 0x2780, v131
	v_pk_mul_f32 v[118:119], v[114:115], v[118:119]
	v_mul_f32_e32 v132, 0x45800000, v130
	v_cndmask_b32_e32 v130, v130, v132, vcc
	v_mul_f32_e32 v136, 0xbfb8aa3b, v130
	v_mul_f32_e32 v131, v136, v120
	v_exp_f32_e32 v131, v131
	v_mul_f32_e32 v122, v136, v122
	v_mul_f32_e32 v123, v136, v123
	v_exp_f32_e32 v122, v122
	v_add_f32_e32 v131, 1.0, v131
	v_rcp_f32_e32 v134, v131
	v_mul_f32_e32 v131, v136, v121
	v_exp_f32_e32 v131, v131
	v_exp_f32_e32 v123, v123
	v_add_f32_e32 v122, 1.0, v122
	v_rcp_f32_e32 v122, v122
	v_add_f32_e32 v131, 1.0, v131
	v_add_f32_e32 v123, 1.0, v123
	v_rcp_f32_e32 v135, v131
	v_rcp_f32_e32 v123, v123
	v_mul_f32_e32 v130, v130, v130
	v_pk_mul_f32 v[120:121], v[120:121], v[124:125]
	v_pk_mul_f32 v[124:125], v[130:131], v[134:135] op_sel_hi:[0,1]
	v_pk_mul_f32 v[122:123], v[130:131], v[122:123] op_sel_hi:[0,1]
	v_pk_mul_f32 v[120:121], v[124:125], v[120:121]
	v_pk_mul_f32 v[122:123], v[122:123], v[126:127]
	v_cvt_pk_bf16_f32 v120, v120, v121
	v_cvt_pk_bf16_f32 v121, v122, v123
	v_mul_f32_e32 v122, v136, v112
	v_mul_f32_e32 v123, v136, v113
	v_exp_f32_e32 v122, v122
	v_exp_f32_e32 v123, v123
	v_pk_mul_f32 v[112:113], v[112:113], v[116:117]
	v_mul_f32_e32 v114, v136, v114
	v_add_f32_e32 v122, 1.0, v122
	v_add_f32_e32 v123, 1.0, v123
	v_rcp_f32_e32 v122, v122
	v_rcp_f32_e32 v123, v123
	v_mul_f32_e32 v115, v136, v115
	v_exp_f32_e32 v114, v114
	v_exp_f32_e32 v115, v115
	v_pk_mul_f32 v[116:117], v[130:131], v[122:123] op_sel_hi:[0,1]
	v_pk_mul_f32 v[112:113], v[116:117], v[112:113]
	v_fmamk_f32 v116, v241, 0x3a000000, v234
	v_cmp_gt_f32_e32 vcc, s78, v116
	v_mul_f32_e32 v117, 0x4b800000, v116
	v_add_f32_e32 v114, 1.0, v114
	v_cndmask_b32_e32 v116, v116, v117, vcc
	v_rsq_f32_e32 v116, v116
	v_add_f32_e32 v115, 1.0, v115
	v_rcp_f32_e32 v114, v114
	v_rcp_f32_e32 v115, v115
	v_mul_f32_e32 v117, 0x45800000, v116
	v_cndmask_b32_e32 v116, v116, v117, vcc
	v_mul_f32_e32 v117, 0xbfb8aa3b, v116
	v_pk_mul_f32 v[114:115], v[130:131], v[114:115] op_sel_hi:[0,1]
	v_pk_mul_f32 v[114:115], v[114:115], v[118:119]
	v_mul_f32_e32 v118, v117, v104
	v_mul_f32_e32 v119, v117, v105
	v_pk_mul_f32 v[110:111], v[106:107], v[110:111]
	v_mul_f32_e32 v106, v117, v106
	v_mul_f32_e32 v107, v117, v107
	v_exp_f32_e32 v118, v118
	v_exp_f32_e32 v119, v119
	v_exp_f32_e32 v106, v106
	v_exp_f32_e32 v107, v107
	v_add_f32_e32 v118, 1.0, v118
	v_add_f32_e32 v119, 1.0, v119
	v_add_f32_e32 v106, 1.0, v106
	v_add_f32_e32 v107, 1.0, v107
	v_rcp_f32_e32 v118, v118
	v_rcp_f32_e32 v119, v119
	v_rcp_f32_e32 v106, v106
	v_rcp_f32_e32 v107, v107
	v_mul_f32_e32 v116, v116, v116
	v_pk_mul_f32 v[104:105], v[104:105], v[108:109]
	v_pk_mul_f32 v[108:109], v[116:117], v[118:119] op_sel_hi:[0,1]
	v_pk_mul_f32 v[106:107], v[116:117], v[106:107] op_sel_hi:[0,1]
	v_pk_mul_f32 v[104:105], v[108:109], v[104:105]
	v_pk_mul_f32 v[106:107], v[106:107], v[110:111]
	v_cvt_pk_bf16_f32 v104, v104, v105
	v_cvt_pk_bf16_f32 v105, v106, v107
	v_mul_f32_e32 v106, v117, v96
	v_mul_f32_e32 v107, v117, v97
	v_exp_f32_e32 v106, v106
	v_exp_f32_e32 v107, v107
	v_pk_mul_f32 v[102:103], v[98:99], v[102:103]
	v_mul_f32_e32 v98, v117, v98
	v_add_f32_e32 v106, 1.0, v106
	v_add_f32_e32 v107, 1.0, v107
	v_rcp_f32_e32 v106, v106
	v_rcp_f32_e32 v107, v107
	v_mul_f32_e32 v99, v117, v99
	v_pk_mul_f32 v[96:97], v[96:97], v[100:101]
	v_exp_f32_e32 v98, v98
	v_pk_mul_f32 v[100:101], v[116:117], v[106:107] op_sel_hi:[0,1]
	v_exp_f32_e32 v99, v99
	v_pk_mul_f32 v[96:97], v[100:101], v[96:97]
	v_add_f32_e32 v98, 1.0, v98
	v_cvt_pk_bf16_f32 v106, v96, v97
	v_fmamk_f32 v96, v240, 0x3a000000, v234
	v_cmp_gt_f32_e32 vcc, s78, v96
	v_mul_f32_e32 v97, 0x4b800000, v96
	v_add_f32_e32 v99, 1.0, v99
	v_cndmask_b32_e32 v96, v96, v97, vcc
	v_rcp_f32_e32 v98, v98
	v_rcp_f32_e32 v99, v99
	v_rsq_f32_e32 v96, v96
	v_pk_mul_f32 v[94:95], v[90:91], v[94:95]
; template <int K, int EPI, bool MIX = false>
; __device__ __forceinline__ void gemm_phase(const Params& p, const u16* __restrict__ A, const u16* __restrict__ Bt,
;                            const float* __restrict__ rs_in, float* __restrict__ ssq_out, float alpha, bool rev = false) {
;     ...
;     if constexpr (EPI == EPI_SWIGLU) {
; #pragma unroll
;       for (int ai = 0; ai < 2; ++ai)
; #pragma unroll
;         for (int m = 0; m < 4; ++m) {
;           int row = brow + ai * 128 + wr * 64 + m * 16 + fr_e;
;           const float rs = rsqrtf(rsq[ai][m] * (1.f / DM) + 1e-6f);
;           const float c1 = rs * -1.4426950408889634f, rs2 = rs * rs;
;           u16* orow = p.Bbuf + blk_off(row, cpn * 128 + wc * 32, DFF) + wn16;
;           uint2 o2[2];
; #pragma unroll
;           for (int n = 0; n < 2; ++n) {
;             f32x4 g = acc[ai][0][m][n], u = acc[ai][1][m][n];
;             float h[4];
; #pragma unroll
;             for (int j = 0; j < 4; ++j) h[j] = (g[j] * u[j]) * (rs2 * __builtin_amdgcn_rcpf(1.f + __builtin_amdgcn_exp2f(g[j] * c1)));
;             o2[n].x = pk2(h[0], h[1]); o2[n].y = pk2(h[2], h[3]);
;           }
;           *(uint4*)orow = widen_pair(o2[0], o2[1]);
;         }
	v_pk_mul_f32 v[86:87], v[82:83], v[86:87]
	v_pk_mul_f32 v[98:99], v[116:117], v[98:99] op_sel_hi:[0,1]
	v_mul_f32_e32 v97, 0x45800000, v96
	v_pk_mul_f32 v[98:99], v[98:99], v[102:103]
	v_cndmask_b32_e32 v96, v96, v97, vcc
	v_cvt_pk_bf16_f32 v107, v98, v99
	v_mul_f32_e32 v99, 0xbfb8aa3b, v96
	v_mul_f32_e32 v102, v99, v88
	v_mul_f32_e32 v103, v99, v89
	v_mul_f32_e32 v90, v99, v90
	v_mul_f32_e32 v91, v99, v91
	v_exp_f32_e32 v102, v102
	v_exp_f32_e32 v103, v103
	v_exp_f32_e32 v90, v90
	v_exp_f32_e32 v91, v91
	v_add_f32_e32 v102, 1.0, v102
	v_add_f32_e32 v103, 1.0, v103
	v_add_f32_e32 v90, 1.0, v90
	v_add_f32_e32 v91, 1.0, v91
	v_rcp_f32_e32 v102, v102
	v_rcp_f32_e32 v103, v103
	v_rcp_f32_e32 v90, v90
	v_rcp_f32_e32 v91, v91
	v_mul_f32_e32 v98, v96, v96
	v_pk_mul_f32 v[88:89], v[88:89], v[92:93]
	v_pk_mul_f32 v[92:93], v[98:99], v[102:103] op_sel_hi:[0,1]
	v_pk_mul_f32 v[90:91], v[98:99], v[90:91] op_sel_hi:[0,1]
	v_pk_mul_f32 v[88:89], v[92:93], v[88:89]
	v_pk_mul_f32 v[90:91], v[90:91], v[94:95]
	v_cvt_pk_bf16_f32 v88, v88, v89
	v_cvt_pk_bf16_f32 v89, v90, v91
	v_mul_f32_e32 v90, v99, v80
	v_mul_f32_e32 v91, v99, v81
	v_mul_f32_e32 v82, v99, v82
	v_mul_f32_e32 v83, v99, v83
	s_lshl_b32 s38, s80, 7
	v_exp_f32_e32 v90, v90
	v_exp_f32_e32 v91, v91
	v_exp_f32_e32 v82, v82
	v_exp_f32_e32 v83, v83
	s_or_b32 s38, s38, s51
	s_ashr_i32 s80, s38, 6
	s_ashr_i32 s38, s41, 7
	s_mulk_i32 s38, 0x58
	s_ashr_i32 s81, s80, 31
	s_ashr_i32 s39, s38, 31
	v_add_f32_e32 v90, 1.0, v90
	v_add_f32_e32 v91, 1.0, v91
	v_add_f32_e32 v82, 1.0, v82
	v_add_f32_e32 v83, 1.0, v83
	s_add_u32 s38, s38, s80
	v_rcp_f32_e32 v90, v90
	v_rcp_f32_e32 v91, v91
	v_rcp_f32_e32 v82, v82
	v_rcp_f32_e32 v83, v83
	s_addc_u32 s39, s39, s81
	s_lshl_b64 s[38:39], s[38:39], 14
	s_add_u32 s38, s92, s38
	s_addc_u32 s39, s93, s39
	v_or_b32_e32 v96, 0x1000, v210
	v_mov_b32_e32 v97, v211
	v_pk_mul_f32 v[80:81], v[80:81], v[84:85]
	v_pk_mul_f32 v[84:85], v[98:99], v[90:91] op_sel_hi:[0,1]
	v_pk_mul_f32 v[82:83], v[98:99], v[82:83] op_sel_hi:[0,1]
	v_ashrrev_i32_e32 v129, 31, v128
	v_lshl_add_u64 v[100:101], s[38:39], 0, v[96:97]
	v_pk_mul_f32 v[80:81], v[84:85], v[80:81]
	v_pk_mul_f32 v[82:83], v[82:83], v[86:87]
	v_cvt_pk_bf16_f32 v122, v112, v113
	v_lshlrev_b64 v[112:113], 1, v[128:129]
	v_lshl_add_u64 v[100:101], v[100:101], 0, s[20:21]
	v_cvt_pk_bf16_f32 v90, v80, v81
	v_cvt_pk_bf16_f32 v91, v82, v83
	v_lshl_add_u64 v[80:81], v[100:101], 0, v[112:113]
	v_permlane32_swap_b32_e32 v88, v90
	v_permlane32_swap_b32_e32 v89, v91
	global_store_dwordx4 v[80:81], v[88:91], off
	v_fmamk_f32 v80, v239, 0x3a000000, v234
	v_cmp_gt_f32_e32 vcc, s78, v80
	v_mul_f32_e32 v81, 0x4b800000, v80
	v_pk_mul_f32 v[78:79], v[74:75], v[78:79]
	v_cndmask_b32_e32 v80, v80, v81, vcc
	v_rsq_f32_e32 v80, v80
	v_pk_mul_f32 v[70:71], v[66:67], v[70:71]
	v_pk_mul_f32 v[62:63], v[58:59], v[62:63]
	v_pk_mul_f32 v[54:55], v[50:51], v[54:55]
	v_mul_f32_e32 v81, 0x45800000, v80
	v_cndmask_b32_e32 v80, v80, v81, vcc
	v_mul_f32_e32 v83, 0xbfb8aa3b, v80
	v_mul_f32_e32 v86, v83, v72
	v_mul_f32_e32 v87, v83, v73
	v_mul_f32_e32 v74, v83, v74
	v_mul_f32_e32 v75, v83, v75
	v_exp_f32_e32 v86, v86
	v_exp_f32_e32 v87, v87
	v_exp_f32_e32 v74, v74
	v_exp_f32_e32 v75, v75
	v_add_f32_e32 v86, 1.0, v86
	v_add_f32_e32 v87, 1.0, v87
	v_add_f32_e32 v74, 1.0, v74
	v_add_f32_e32 v75, 1.0, v75
	v_rcp_f32_e32 v86, v86
	v_rcp_f32_e32 v87, v87
	v_rcp_f32_e32 v74, v74
	v_rcp_f32_e32 v75, v75
	v_mul_f32_e32 v82, v80, v80
	v_pk_mul_f32 v[72:73], v[72:73], v[76:77]
	v_pk_mul_f32 v[76:77], v[82:83], v[86:87] op_sel_hi:[0,1]
	v_pk_mul_f32 v[74:75], v[82:83], v[74:75] op_sel_hi:[0,1]
	v_pk_mul_f32 v[72:73], v[76:77], v[72:73]
	v_pk_mul_f32 v[74:75], v[74:75], v[78:79]
	v_cvt_pk_bf16_f32 v72, v72, v73
	v_cvt_pk_bf16_f32 v73, v74, v75
	v_mul_f32_e32 v74, v83, v64
	v_mul_f32_e32 v75, v83, v65
	v_mul_f32_e32 v66, v83, v66
	v_mul_f32_e32 v67, v83, v67
	v_exp_f32_e32 v74, v74
	v_exp_f32_e32 v75, v75
	v_exp_f32_e32 v66, v66
	v_exp_f32_e32 v67, v67
	v_add_f32_e32 v74, 1.0, v74
	v_add_f32_e32 v75, 1.0, v75
	v_add_f32_e32 v66, 1.0, v66
	v_add_f32_e32 v67, 1.0, v67
	v_rcp_f32_e32 v74, v74
	v_rcp_f32_e32 v75, v75
	v_rcp_f32_e32 v66, v66
	v_rcp_f32_e32 v67, v67
	v_or_b32_e32 v80, 0x1800, v210
	v_mov_b32_e32 v81, v211
	v_pk_mul_f32 v[64:65], v[64:65], v[68:69]
	v_pk_mul_f32 v[68:69], v[82:83], v[74:75] op_sel_hi:[0,1]
	v_pk_mul_f32 v[66:67], v[82:83], v[66:67] op_sel_hi:[0,1]
	v_lshl_add_u64 v[84:85], s[38:39], 0, v[80:81]
	v_pk_mul_f32 v[64:65], v[68:69], v[64:65]
	v_pk_mul_f32 v[66:67], v[66:67], v[70:71]
	v_lshl_add_u64 v[84:85], v[84:85], 0, s[20:21]
	v_cvt_pk_bf16_f32 v74, v64, v65
	v_cvt_pk_bf16_f32 v75, v66, v67
	v_lshl_add_u64 v[64:65], v[84:85], 0, v[112:113]
	v_permlane32_swap_b32_e32 v72, v74
	v_permlane32_swap_b32_e32 v73, v75
	global_store_dwordx4 v[64:65], v[72:75], off
	v_fmamk_f32 v64, v238, 0x3a000000, v234
	v_cmp_gt_f32_e32 vcc, s78, v64
	v_mul_f32_e32 v65, 0x4b800000, v64
	v_pk_mul_f32 v[46:47], v[42:43], v[46:47]
	v_cndmask_b32_e32 v64, v64, v65, vcc
	v_rsq_f32_e32 v64, v64
	v_pk_mul_f32 v[30:31], v[26:27], v[30:31]
	v_pk_mul_f32 v[38:39], v[34:35], v[38:39]
	v_pk_mul_f32 v[22:23], v[18:19], v[22:23]
	v_mul_f32_e32 v65, 0x45800000, v64
	v_cndmask_b32_e32 v64, v64, v65, vcc
	v_mul_f32_e32 v65, 0xbfb8aa3b, v64
	v_mul_f32_e32 v68, v65, v56
	v_mul_f32_e32 v69, v65, v57
	v_mul_f32_e32 v58, v65, v58
	v_mul_f32_e32 v59, v65, v59
	v_exp_f32_e32 v68, v68
	v_exp_f32_e32 v69, v69
	v_exp_f32_e32 v58, v58
	v_exp_f32_e32 v59, v59
	v_add_f32_e32 v68, 1.0, v68
	v_add_f32_e32 v69, 1.0, v69
	v_add_f32_e32 v58, 1.0, v58
	v_add_f32_e32 v59, 1.0, v59
	v_rcp_f32_e32 v68, v68
; template <int K, int EPI, bool MIX = false>
; __device__ __forceinline__ void gemm_phase(const Params& p, const u16* __restrict__ A, const u16* __restrict__ Bt,
;                            const float* __restrict__ rs_in, float* __restrict__ ssq_out, float alpha, bool rev = false) {
;     ...
;     if constexpr (EPI == EPI_SWIGLU) {
; #pragma unroll
;       for (int ai = 0; ai < 2; ++ai)
; #pragma unroll
;         for (int m = 0; m < 4; ++m) {
;           int row = brow + ai * 128 + wr * 64 + m * 16 + fr_e;
;           const float rs = rsqrtf(rsq[ai][m] * (1.f / DM) + 1e-6f);
;           const float c1 = rs * -1.4426950408889634f, rs2 = rs * rs;
;           u16* orow = p.Bbuf + blk_off(row, cpn * 128 + wc * 32, DFF) + wn16;
;           uint2 o2[2];
; #pragma unroll
;           for (int n = 0; n < 2; ++n) {
;             f32x4 g = acc[ai][0][m][n], u = acc[ai][1][m][n];
;             float h[4];
; #pragma unroll
;             for (int j = 0; j < 4; ++j) h[j] = (g[j] * u[j]) * (rs2 * __builtin_amdgcn_rcpf(1.f + __builtin_amdgcn_exp2f(g[j] * c1)));
;             o2[n].x = pk2(h[0], h[1]); o2[n].y = pk2(h[2], h[3]);
;           }
;           *(uint4*)orow = widen_pair(o2[0], o2[1]);
;         }
	v_rcp_f32_e32 v69, v69
	v_rcp_f32_e32 v58, v58
	v_rcp_f32_e32 v59, v59
	v_mul_f32_e32 v64, v64, v64
	v_pk_mul_f32 v[56:57], v[56:57], v[60:61]
	v_pk_mul_f32 v[60:61], v[64:65], v[68:69] op_sel_hi:[0,1]
	v_pk_mul_f32 v[58:59], v[64:65], v[58:59] op_sel_hi:[0,1]
	v_mul_f32_e32 v50, v65, v50
	v_mul_f32_e32 v51, v65, v51
	v_pk_mul_f32 v[56:57], v[60:61], v[56:57]
	v_pk_mul_f32 v[58:59], v[58:59], v[62:63]
	v_exp_f32_e32 v50, v50
	v_exp_f32_e32 v51, v51
	v_cvt_pk_bf16_f32 v56, v56, v57
	v_cvt_pk_bf16_f32 v57, v58, v59
	v_mul_f32_e32 v58, v65, v48
	v_mul_f32_e32 v59, v65, v49
	v_exp_f32_e32 v58, v58
	v_exp_f32_e32 v59, v59
	v_add_f32_e32 v50, 1.0, v50
	v_add_f32_e32 v51, 1.0, v51
	v_rcp_f32_e32 v50, v50
	v_rcp_f32_e32 v51, v51
	v_add_f32_e32 v58, 1.0, v58
	v_add_f32_e32 v59, 1.0, v59
	v_rcp_f32_e32 v58, v58
	v_rcp_f32_e32 v59, v59
	v_pk_mul_f32 v[50:51], v[64:65], v[50:51] op_sel_hi:[0,1]
	v_pk_mul_f32 v[50:51], v[50:51], v[54:55]
	v_pk_mul_f32 v[48:49], v[48:49], v[52:53]
	v_pk_mul_f32 v[52:53], v[64:65], v[58:59] op_sel_hi:[0,1]
	v_cvt_pk_bf16_f32 v59, v50, v51
	v_fmamk_f32 v50, v237, 0x3a000000, v234
	v_cmp_gt_f32_e32 vcc, s78, v50
	v_mul_f32_e32 v51, 0x4b800000, v50
	v_pk_mul_f32 v[48:49], v[52:53], v[48:49]
	v_cndmask_b32_e32 v50, v50, v51, vcc
	v_rsq_f32_e32 v50, v50
	s_addk_i32 s41, 0x80
	v_lshl_add_u64 v[132:133], s[38:39], 0, v[210:211]
	s_ashr_i32 s38, s41, 7
	v_mul_f32_e32 v51, 0x45800000, v50
	v_cndmask_b32_e32 v50, v50, v51, vcc
	v_mul_f32_e32 v51, 0xbfb8aa3b, v50
	v_mul_f32_e32 v52, v51, v40
	v_mul_f32_e32 v53, v51, v41
	v_mul_f32_e32 v42, v51, v42
	v_mul_f32_e32 v43, v51, v43
	v_exp_f32_e32 v52, v52
	v_exp_f32_e32 v53, v53
	v_exp_f32_e32 v42, v42
	v_exp_f32_e32 v43, v43
	v_add_f32_e32 v52, 1.0, v52
	v_add_f32_e32 v53, 1.0, v53
	v_add_f32_e32 v42, 1.0, v42
	v_add_f32_e32 v43, 1.0, v43
	v_rcp_f32_e32 v52, v52
	v_rcp_f32_e32 v53, v53
	v_rcp_f32_e32 v42, v42
	v_rcp_f32_e32 v43, v43
	v_mul_f32_e32 v50, v50, v50
	v_pk_mul_f32 v[40:41], v[40:41], v[44:45]
	v_pk_mul_f32 v[44:45], v[50:51], v[52:53] op_sel_hi:[0,1]
	v_pk_mul_f32 v[42:43], v[50:51], v[42:43] op_sel_hi:[0,1]
	v_pk_mul_f32 v[40:41], v[44:45], v[40:41]
	v_pk_mul_f32 v[42:43], v[42:43], v[46:47]
	v_cvt_pk_bf16_f32 v40, v40, v41
	v_cvt_pk_bf16_f32 v41, v42, v43
	v_mul_f32_e32 v42, v51, v32
	v_mul_f32_e32 v43, v51, v33
	v_exp_f32_e32 v42, v42
	v_exp_f32_e32 v43, v43
	v_pk_mul_f32 v[32:33], v[32:33], v[36:37]
	v_mul_f32_e32 v34, v51, v34
	v_add_f32_e32 v42, 1.0, v42
	v_add_f32_e32 v43, 1.0, v43
	v_rcp_f32_e32 v42, v42
	v_rcp_f32_e32 v43, v43
	v_mul_f32_e32 v35, v51, v35
	v_exp_f32_e32 v34, v34
	v_exp_f32_e32 v35, v35
	v_pk_mul_f32 v[36:37], v[50:51], v[42:43] op_sel_hi:[0,1]
	v_pk_mul_f32 v[32:33], v[36:37], v[32:33]
	s_mulk_i32 s38, 0x58
	v_cvt_pk_bf16_f32 v42, v32, v33
	v_fmamk_f32 v32, v236, 0x3a000000, v234
	v_cmp_gt_f32_e32 vcc, s78, v32
	v_mul_f32_e32 v33, 0x4b800000, v32
	v_add_f32_e32 v34, 1.0, v34
	v_cndmask_b32_e32 v32, v32, v33, vcc
	v_rsq_f32_e32 v32, v32
	v_add_f32_e32 v35, 1.0, v35
	s_ashr_i32 s39, s38, 31
	v_rcp_f32_e32 v34, v34
	v_mul_f32_e32 v33, 0x45800000, v32
	v_cndmask_b32_e32 v32, v32, v33, vcc
	v_mul_f32_e32 v33, 0xbfb8aa3b, v32
	v_mul_f32_e32 v36, v33, v24
	v_mul_f32_e32 v37, v33, v25
	v_mul_f32_e32 v26, v33, v26
	v_mul_f32_e32 v27, v33, v27
	v_exp_f32_e32 v36, v36
	v_exp_f32_e32 v37, v37
	v_exp_f32_e32 v26, v26
	v_exp_f32_e32 v27, v27
	v_add_f32_e32 v36, 1.0, v36
	v_add_f32_e32 v37, 1.0, v37
	v_add_f32_e32 v26, 1.0, v26
	v_add_f32_e32 v27, 1.0, v27
	v_rcp_f32_e32 v36, v36
	v_rcp_f32_e32 v37, v37
	v_rcp_f32_e32 v26, v26
	v_rcp_f32_e32 v27, v27
	v_mul_f32_e32 v32, v32, v32
	v_pk_mul_f32 v[24:25], v[24:25], v[28:29]
	v_pk_mul_f32 v[28:29], v[32:33], v[36:37] op_sel_hi:[0,1]
	v_pk_mul_f32 v[26:27], v[32:33], v[26:27] op_sel_hi:[0,1]
	v_pk_mul_f32 v[24:25], v[28:29], v[24:25]
	v_pk_mul_f32 v[26:27], v[26:27], v[30:31]
	v_cvt_pk_bf16_f32 v24, v24, v25
	v_cvt_pk_bf16_f32 v25, v26, v27
	v_mul_f32_e32 v26, v33, v16
	v_mul_f32_e32 v27, v33, v17
	v_mul_f32_e32 v18, v33, v18
	v_mul_f32_e32 v19, v33, v19
	v_exp_f32_e32 v26, v26
	v_exp_f32_e32 v27, v27
	v_exp_f32_e32 v18, v18
; #define SCHED __builtin_amdgcn_sched_barrier(0)
; template <int K, int EPI, bool MIX = false>
; __device__ __forceinline__ void gemm_phase(const Params& p, const u16* __restrict__ A, const u16* __restrict__ Bt,
;                            const float* __restrict__ rs_in, float* __restrict__ ssq_out, float alpha, bool rev = false) {
;     ...
;     if constexpr (EPI == EPI_SWIGLU) {
; #pragma unroll
;       for (int ai = 0; ai < 2; ++ai)
; #pragma unroll
;         for (int m = 0; m < 4; ++m) {
;           int row = brow + ai * 128 + wr * 64 + m * 16 + fr_e;
;           const float rs = rsqrtf(rsq[ai][m] * (1.f / DM) + 1e-6f);
;           const float c1 = rs * -1.4426950408889634f, rs2 = rs * rs;
;           u16* orow = p.Bbuf + blk_off(row, cpn * 128 + wc * 32, DFF) + wn16;
;           uint2 o2[2];
; #pragma unroll
;           for (int n = 0; n < 2; ++n) {
;             f32x4 g = acc[ai][0][m][n], u = acc[ai][1][m][n];
;             float h[4];
; #pragma unroll
;             for (int j = 0; j < 4; ++j) h[j] = (g[j] * u[j]) * (rs2 * __builtin_amdgcn_rcpf(1.f + __builtin_amdgcn_exp2f(g[j] * c1)));
;             o2[n].x = pk2(h[0], h[1]); o2[n].y = pk2(h[2], h[3]);
;           }
;           *(uint4*)orow = widen_pair(o2[0], o2[1]);
;         }
;     ...
;     if (!more) break;
;     asm volatile("" ::: "memory");
;     SCHED;
;   }
	v_exp_f32_e32 v19, v19
	v_rcp_f32_e32 v35, v35
	v_add_f32_e32 v26, 1.0, v26
	v_add_f32_e32 v27, 1.0, v27
	v_add_f32_e32 v18, 1.0, v18
	v_add_f32_e32 v19, 1.0, v19
	s_add_u32 s38, s38, s80
	v_rcp_f32_e32 v26, v26
	v_rcp_f32_e32 v27, v27
	v_rcp_f32_e32 v18, v18
	v_rcp_f32_e32 v19, v19
	s_addc_u32 s39, s39, s81
	s_lshl_b64 s[38:39], s[38:39], 14
	s_add_u32 s38, s92, s38
	v_pk_mul_f32 v[34:35], v[50:51], v[34:35] op_sel_hi:[0,1]
	s_addc_u32 s39, s93, s39
	v_pk_mul_f32 v[34:35], v[34:35], v[38:39]
	v_pk_mul_f32 v[16:17], v[16:17], v[20:21]
	v_pk_mul_f32 v[20:21], v[32:33], v[26:27] op_sel_hi:[0,1]
	v_pk_mul_f32 v[18:19], v[32:33], v[18:19] op_sel_hi:[0,1]
	v_cvt_pk_bf16_f32 v43, v34, v35
	v_lshl_add_u64 v[34:35], s[38:39], 0, v[96:97]
	v_pk_mul_f32 v[16:17], v[20:21], v[16:17]
	v_pk_mul_f32 v[18:19], v[18:19], v[22:23]
	v_lshl_add_u64 v[34:35], v[34:35], 0, s[20:21]
	v_cvt_pk_bf16_f32 v26, v16, v17
	v_cvt_pk_bf16_f32 v27, v18, v19
	v_lshl_add_u64 v[16:17], v[34:35], 0, v[112:113]
	v_permlane32_swap_b32_e32 v24, v26
	v_permlane32_swap_b32_e32 v25, v27
	global_store_dwordx4 v[16:17], v[24:27], off
	v_fmamk_f32 v16, v235, 0x3a000000, v234
	v_cmp_gt_f32_e32 vcc, s78, v16
	v_mul_f32_e32 v17, 0x4b800000, v16
	v_pk_mul_f32 v[14:15], v[10:11], v[14:15]
	v_cndmask_b32_e32 v16, v16, v17, vcc
	v_rsq_f32_e32 v16, v16
	v_pk_mul_f32 v[6:7], v[2:3], v[6:7]
	v_lshl_add_u64 v[66:67], s[38:39], 0, v[210:211]
	v_lshl_add_u64 v[18:19], s[38:39], 0, v[80:81]
	v_mul_f32_e32 v17, 0x45800000, v16
	v_cndmask_b32_e32 v16, v16, v17, vcc
	v_mul_f32_e32 v17, 0xbfb8aa3b, v16
	v_mul_f32_e32 v20, v17, v8
	v_mul_f32_e32 v21, v17, v9
	v_mul_f32_e32 v10, v17, v10
	v_mul_f32_e32 v11, v17, v11
	v_exp_f32_e32 v20, v20
	v_exp_f32_e32 v21, v21
	v_exp_f32_e32 v10, v10
	v_exp_f32_e32 v11, v11
	v_add_f32_e32 v20, 1.0, v20
	v_add_f32_e32 v21, 1.0, v21
	v_add_f32_e32 v10, 1.0, v10
	v_add_f32_e32 v11, 1.0, v11
	v_rcp_f32_e32 v20, v20
	v_rcp_f32_e32 v21, v21
	v_rcp_f32_e32 v10, v10
	v_rcp_f32_e32 v11, v11
	v_mul_f32_e32 v16, v16, v16
	v_pk_mul_f32 v[8:9], v[8:9], v[12:13]
	v_pk_mul_f32 v[12:13], v[16:17], v[20:21] op_sel_hi:[0,1]
	v_pk_mul_f32 v[10:11], v[16:17], v[10:11] op_sel_hi:[0,1]
	v_pk_mul_f32 v[8:9], v[12:13], v[8:9]
	v_pk_mul_f32 v[10:11], v[10:11], v[14:15]
	v_cvt_pk_bf16_f32 v8, v8, v9
	v_cvt_pk_bf16_f32 v9, v10, v11
	v_mul_f32_e32 v10, v17, v0
	v_mul_f32_e32 v11, v17, v1
	v_mul_f32_e32 v2, v17, v2
	v_mul_f32_e32 v3, v17, v3
	v_exp_f32_e32 v10, v10
	v_exp_f32_e32 v11, v11
	v_exp_f32_e32 v2, v2
	v_exp_f32_e32 v3, v3
	v_add_f32_e32 v10, 1.0, v10
	v_add_f32_e32 v11, 1.0, v11
	v_add_f32_e32 v2, 1.0, v2
	v_add_f32_e32 v3, 1.0, v3
	v_rcp_f32_e32 v10, v10
	v_rcp_f32_e32 v11, v11
	v_rcp_f32_e32 v2, v2
	v_rcp_f32_e32 v3, v3
	v_pk_mul_f32 v[0:1], v[0:1], v[4:5]
	v_pk_mul_f32 v[4:5], v[16:17], v[10:11] op_sel_hi:[0,1]
	v_pk_mul_f32 v[0:1], v[4:5], v[0:1]
	v_pk_mul_f32 v[2:3], v[16:17], v[2:3] op_sel_hi:[0,1]
	v_pk_mul_f32 v[2:3], v[2:3], v[6:7]
	v_lshl_add_u64 v[132:133], v[132:133], 0, s[20:21]
	v_cvt_pk_bf16_f32 v123, v114, v115
	v_lshl_add_u64 v[66:67], v[66:67], 0, s[20:21]
	v_cvt_pk_bf16_f32 v58, v48, v49
	v_lshl_add_u64 v[18:19], v[18:19], 0, s[20:21]
	v_cvt_pk_bf16_f32 v10, v0, v1
	v_cvt_pk_bf16_f32 v11, v2, v3
	v_lshl_add_u64 v[114:115], v[132:133], 0, v[112:113]
	v_permlane32_swap_b32_e32 v120, v122
	v_permlane32_swap_b32_e32 v121, v123
	v_permlane32_swap_b32_e32 v104, v106
	v_permlane32_swap_b32_e32 v105, v107
	v_lshl_add_u64 v[48:49], v[66:67], 0, v[112:113]
	v_permlane32_swap_b32_e32 v56, v58
	v_permlane32_swap_b32_e32 v57, v59
	v_permlane32_swap_b32_e32 v40, v42
	v_permlane32_swap_b32_e32 v41, v43
	v_lshl_add_u64 v[0:1], v[18:19], 0, v[112:113]
	v_permlane32_swap_b32_e32 v8, v10
	v_permlane32_swap_b32_e32 v9, v11
	s_mov_b64 s[38:39], -1
	s_and_b64 vcc, exec, s[4:5]
	global_store_dwordx4 v[114:115], v[120:123], off
	global_store_dwordx4 v[114:115], v[104:107], off offset:2048
	global_store_dwordx4 v[48:49], v[56:59], off
	global_store_dwordx4 v[48:49], v[40:43], off offset:2048
	global_store_dwordx4 v[0:1], v[8:11], off
	s_cbranch_vccnz .LBB0_87
	s_mov_b64 s[38:39], 0
	s_branch .LBB0_87

; #define SCHED __builtin_amdgcn_sched_barrier(0)
; template <int K, int EPI, bool MIX = false>
; __device__ __forceinline__ void gemm_phase(const Params& p, const u16* __restrict__ A, const u16* __restrict__ Bt,
;                            const float* __restrict__ rs_in, float* __restrict__ ssq_out, float alpha, bool rev = false) {
;     ...
;   for (;;) {
;     f32x4 acc[2][2][4][2];
; #pragma unroll
;     for (int a = 0; a < 2; ++a)
; #pragma unroll
;       for (int b = 0; b < 2; ++b)
; #pragma unroll
;         for (int m = 0; m < 4; ++m)
; #pragma unroll
;           for (int n = 0; n < 2; ++n) acc[a][b][m][n] = f32x4{0.f, 0.f, 0.f, 0.f};
;     bf16x8 At[4][2], B0[2][2], B1[2][2];
;     asm volatile("" ::: "memory");
;     SCHED;
.LBB0_126:
	s_andn2_b64 vcc, exec, s[4:5]
	s_cbranch_vccz .LBB0_167
	s_and_b64 vcc, exec, s[24:25]
	s_cbranch_vccnz .Llate_p2_done
	s_barrier
.Llate_p2_done:
.LBB0_127:
	s_mov_b32 s82, s80
	s_mov_b32 s81, s79
	v_mov_b32_e32 v0, 0
	s_mov_b32 s79, -2
	s_mov_b64 s[4:5], s[10:11]
	s_mov_b64 s[46:47], s[2:3]
	s_mov_b64 s[62:63], s[8:9]
	s_waitcnt lgkmcnt(0)
	v_mov_b32_e32 v1, v0
	v_mov_b32_e32 v2, v0
	v_mov_b32_e32 v3, v0
	v_mov_b32_e32 v4, v0
	v_mov_b32_e32 v5, v0
	v_mov_b32_e32 v6, v0
	v_mov_b32_e32 v7, v0
	v_mov_b32_e32 v8, v0
	v_mov_b32_e32 v9, v0
	v_mov_b32_e32 v10, v0
	v_mov_b32_e32 v11, v0
	v_mov_b32_e32 v12, v0
	v_mov_b32_e32 v13, v0
	v_mov_b32_e32 v14, v0
	v_mov_b32_e32 v15, v0
	v_mov_b32_e32 v16, v0
	v_mov_b32_e32 v17, v0
	v_mov_b32_e32 v18, v0
	v_mov_b32_e32 v19, v0
	v_mov_b32_e32 v20, v0
	v_mov_b32_e32 v21, v0
	v_mov_b32_e32 v22, v0
	v_mov_b32_e32 v23, v0
	v_mov_b32_e32 v24, v0
	v_mov_b32_e32 v25, v0
	v_mov_b32_e32 v26, v0
	v_mov_b32_e32 v27, v0
	v_mov_b32_e32 v28, v0
	v_mov_b32_e32 v29, v0
	v_mov_b32_e32 v30, v0
	v_mov_b32_e32 v31, v0
	v_mov_b32_e32 v32, v0
	v_mov_b32_e32 v33, v0
	v_mov_b32_e32 v34, v0
	v_mov_b32_e32 v35, v0
	v_mov_b32_e32 v36, v0
	v_mov_b32_e32 v37, v0
	v_mov_b32_e32 v38, v0
	v_mov_b32_e32 v39, v0
	v_mov_b32_e32 v40, v0
	v_mov_b32_e32 v41, v0
	v_mov_b32_e32 v42, v0
	v_mov_b32_e32 v43, v0
	v_mov_b32_e32 v44, v0
	v_mov_b32_e32 v45, v0
	v_mov_b32_e32 v46, v0
	v_mov_b32_e32 v47, v0
	v_mov_b32_e32 v48, v0
	v_mov_b32_e32 v49, v0
	v_mov_b32_e32 v50, v0
	v_mov_b32_e32 v51, v0
	v_mov_b32_e32 v52, v0
	v_mov_b32_e32 v53, v0
	v_mov_b32_e32 v54, v0
	v_mov_b32_e32 v55, v0
	v_mov_b32_e32 v56, v0
	v_mov_b32_e32 v57, v0
	v_mov_b32_e32 v58, v0
	v_mov_b32_e32 v59, v0
	v_mov_b32_e32 v60, v0
	v_mov_b32_e32 v61, v0
	v_mov_b32_e32 v62, v0
	v_mov_b32_e32 v63, v0
	v_mov_b32_e32 v64, v0
	v_mov_b32_e32 v65, v0
	v_mov_b32_e32 v66, v0
	v_mov_b32_e32 v67, v0
	v_mov_b32_e32 v68, v0
	v_mov_b32_e32 v69, v0
	v_mov_b32_e32 v70, v0
	v_mov_b32_e32 v71, v0
	v_mov_b32_e32 v72, v0
	v_mov_b32_e32 v73, v0
	v_mov_b32_e32 v74, v0
	v_mov_b32_e32 v75, v0
	v_mov_b32_e32 v76, v0
	v_mov_b32_e32 v77, v0
	v_mov_b32_e32 v78, v0
	v_mov_b32_e32 v79, v0
	v_mov_b32_e32 v80, v0
	v_mov_b32_e32 v81, v0
	v_mov_b32_e32 v82, v0
	v_mov_b32_e32 v83, v0
	v_mov_b32_e32 v84, v0
	v_mov_b32_e32 v85, v0
	v_mov_b32_e32 v86, v0
	v_mov_b32_e32 v87, v0
	v_mov_b32_e32 v88, v0
	v_mov_b32_e32 v89, v0
	v_mov_b32_e32 v90, v0
	v_mov_b32_e32 v91, v0
	v_mov_b32_e32 v92, v0
	v_mov_b32_e32 v93, v0
	v_mov_b32_e32 v94, v0
	v_mov_b32_e32 v95, v0
	v_mov_b32_e32 v96, v0
	v_mov_b32_e32 v97, v0
	v_mov_b32_e32 v98, v0
	v_mov_b32_e32 v99, v0
	v_mov_b32_e32 v100, v0
	v_mov_b32_e32 v101, v0
	v_mov_b32_e32 v102, v0
	v_mov_b32_e32 v103, v0
	v_mov_b32_e32 v104, v0
	v_mov_b32_e32 v105, v0
	v_mov_b32_e32 v106, v0
	v_mov_b32_e32 v107, v0
	v_mov_b32_e32 v108, v0
	v_mov_b32_e32 v109, v0
	v_mov_b32_e32 v110, v0
	v_mov_b32_e32 v111, v0
	v_mov_b32_e32 v112, v0
	v_mov_b32_e32 v113, v0
	v_mov_b32_e32 v114, v0
	v_mov_b32_e32 v115, v0
	v_mov_b32_e32 v116, v0
	v_mov_b32_e32 v117, v0
	v_mov_b32_e32 v118, v0
	v_mov_b32_e32 v119, v0
	v_mov_b32_e32 v120, v0
	v_mov_b32_e32 v121, v0
	v_mov_b32_e32 v122, v0
	v_mov_b32_e32 v123, v0
	v_mov_b32_e32 v124, v0
	v_mov_b32_e32 v125, v0
	v_mov_b32_e32 v126, v0
	v_mov_b32_e32 v127, v0

; #define MMA(ai,bj,Af,Bf) do{__builtin_amdgcn_s_setprio(1); \
;     _Pragma("unroll") for(int m=0;m<4;++m) _Pragma("unroll") for(int n=0;n<2;++n) _Pragma("unroll") for(int k=0;k<2;++k) \
;       acc[ai][bj][m][n]=__builtin_amdgcn_mfma_f32_16x16x32_bf16(Bf[n][k],Af[m][k],acc[ai][bj][m][n],0,0,0); \
;     __builtin_amdgcn_s_setprio(0);}while(0)
; #define WAIT_V(n) asm volatile("s_waitcnt vmcnt(" #n ")":::"memory")
; #define BAR __builtin_amdgcn_s_barrier()
; #define STAGE_B(b,h,kt) do{ unsigned char* _d = SB(b,h) + wbase; \
;     if constexpr (BLK) { const char* _s = ((h)?baseB1:baseB0) + (size_t)(kt) * 16384; GLDS(_s + voa, _d); GLDS(_s + 8192 + voa, _d + 8192); } \
;     else { const char* _s = ((h)?baseB1:baseB0) + (kt)*128; GLDS(_s + voa, _d); GLDS(_s + (size_t)128*K + voa, _d + 8192); } }while(0)
; template <int K, int EPI, bool MIX = false>
; __device__ __forceinline__ void gemm_phase(const Params& p, const u16* __restrict__ A, const u16* __restrict__ Bt,
;                            const float* __restrict__ rs_in, float* __restrict__ ssq_out, float alpha, bool rev = false) {
;     ...
;       if (more) { STAGE_B(1,1,1); WAIT_V(6); }
;       BAR; MMA(1,1,At,B1); BAR;
;       if (!more && wr == 0) BAR;
.LBB0_147:
	s_barrier
	s_setprio 1
	v_mfma_f32_16x16x32_bf16 v[32:35], v[128:131], v[200:203], v[136:139]
	v_mfma_f32_16x16x32_bf16 v[52:55], v[188:191], v[204:207], v[32:35]
	v_mfma_f32_16x16x32_bf16 v[32:35], v[132:135], v[200:203], v[140:143]
	v_mfma_f32_16x16x32_bf16 v[16:19], v[132:135], v[164:167], v[16:19]
	v_mfma_f32_16x16x32_bf16 v[48:51], v[184:187], v[204:207], v[32:35]
	v_mfma_f32_16x16x32_bf16 v[20:23], v[128:131], v[164:167], v[20:23]
	v_mfma_f32_16x16x32_bf16 v[32:35], v[184:187], v[192:195], v[16:19]
	v_mfma_f32_16x16x32_bf16 v[16:19], v[128:131], v[160:163], v[144:147]
	v_mfma_f32_16x16x32_bf16 v[36:39], v[188:191], v[192:195], v[20:23]
	v_mfma_f32_16x16x32_bf16 v[20:23], v[188:191], v[196:199], v[16:19]
	v_mfma_f32_16x16x32_bf16 v[16:19], v[132:135], v[160:163], v[148:151]
	v_mfma_f32_16x16x32_bf16 v[4:7], v[128:131], v[152:155], v[4:7]
	v_mfma_f32_16x16x32_bf16 v[0:3], v[132:135], v[152:155], v[0:3]
	v_mfma_f32_16x16x32_bf16 v[16:19], v[184:187], v[196:199], v[16:19]
	v_mfma_f32_16x16x32_bf16 v[4:7], v[188:191], v[156:159], v[4:7]
	v_mfma_f32_16x16x32_bf16 v[0:3], v[184:187], v[156:159], v[0:3]
	s_setprio 0
	s_or_b64 vcc, s[4:5], s[24:25]
	s_cbranch_scc0 .Llate_p2_defer
	s_barrier
.Llate_p2_defer:
	s_andn2_b64 vcc, exec, s[46:47]
	s_cbranch_vccnz .LBB0_149
	s_barrier

; #define SCHED __builtin_amdgcn_sched_barrier(0)
; template <int K, int EPI, bool MIX = false>
; __device__ __forceinline__ void gemm_phase(const Params& p, const u16* __restrict__ A, const u16* __restrict__ Bt,
;                            const float* __restrict__ rs_in, float* __restrict__ ssq_out, float alpha, bool rev = false) {
;     ...
;   for (;;) {
;     f32x4 acc[2][2][4][2];
; #pragma unroll
;     for (int a = 0; a < 2; ++a)
; #pragma unroll
;       for (int b = 0; b < 2; ++b)
; #pragma unroll
;         for (int m = 0; m < 4; ++m)
; #pragma unroll
;           for (int n = 0; n < 2; ++n) acc[a][b][m][n] = f32x4{0.f, 0.f, 0.f, 0.f};
;     bf16x8 At[4][2], B0[2][2], B1[2][2];
;     asm volatile("" ::: "memory");
;     SCHED;
.LBB0_181:
	s_andn2_b64 vcc, exec, s[4:5]
	s_cbranch_vccz .LBB0_306
	v_readlane_b32 vcc_lo, v255, 18
	v_readlane_b32 vcc_hi, v255, 19
	s_nop 3
	s_and_b64 vcc, exec, vcc
	s_cbranch_vccnz .Llate_p3_done
	s_barrier
.Llate_p3_done:
.LBB0_182:
	s_mov_b32 s25, s75
	v_mov_b32_e32 v96, 0
	s_mov_b32 s2, -2
	s_mov_b64 s[4:5], s[44:45]
	s_mov_b64 s[6:7], s[16:17]
	s_mov_b64 s[8:9], s[20:21]
	v_mov_b32_e32 v97, v96
	v_mov_b32_e32 v98, v96
	v_mov_b32_e32 v99, v96
	v_mov_b32_e32 v100, v96
	v_mov_b32_e32 v101, v96
	v_mov_b32_e32 v102, v96
	v_mov_b32_e32 v103, v96
	v_mov_b32_e32 v104, v96
	v_mov_b32_e32 v105, v96
	v_mov_b32_e32 v106, v96
	v_mov_b32_e32 v107, v96
	v_mov_b32_e32 v108, v96
	v_mov_b32_e32 v109, v96
	v_mov_b32_e32 v110, v96
	v_mov_b32_e32 v111, v96
	v_mov_b32_e32 v112, v96
	v_mov_b32_e32 v113, v96
	v_mov_b32_e32 v114, v96
	v_mov_b32_e32 v115, v96
	v_mov_b32_e32 v116, v96
	v_mov_b32_e32 v117, v96
	v_mov_b32_e32 v118, v96
	v_mov_b32_e32 v119, v96
	v_mov_b32_e32 v120, v96
	v_mov_b32_e32 v121, v96
	v_mov_b32_e32 v122, v96
	v_mov_b32_e32 v123, v96
	v_mov_b32_e32 v124, v96
	v_mov_b32_e32 v125, v96
	v_mov_b32_e32 v126, v96
	v_mov_b32_e32 v127, v96
	v_mov_b32_e32 v56, v96
	v_mov_b32_e32 v57, v96
	v_mov_b32_e32 v58, v96
	v_mov_b32_e32 v59, v96
	v_mov_b32_e32 v64, v96
	v_mov_b32_e32 v65, v96
	v_mov_b32_e32 v66, v96
	v_mov_b32_e32 v67, v96
	v_mov_b32_e32 v72, v96
	v_mov_b32_e32 v73, v96
	v_mov_b32_e32 v74, v96
	v_mov_b32_e32 v75, v96
	v_mov_b32_e32 v76, v96
	v_mov_b32_e32 v77, v96
	v_mov_b32_e32 v78, v96
	v_mov_b32_e32 v79, v96
	v_mov_b32_e32 v80, v96
	v_mov_b32_e32 v81, v96
	v_mov_b32_e32 v82, v96
	v_mov_b32_e32 v83, v96
	v_mov_b32_e32 v84, v96
	v_mov_b32_e32 v85, v96
	v_mov_b32_e32 v86, v96
	v_mov_b32_e32 v87, v96
	v_mov_b32_e32 v88, v96
	v_mov_b32_e32 v89, v96
	v_mov_b32_e32 v90, v96
	v_mov_b32_e32 v91, v96
	v_mov_b32_e32 v92, v96
	v_mov_b32_e32 v93, v96
	v_mov_b32_e32 v94, v96
	v_mov_b32_e32 v95, v96
	v_mov_b32_e32 v32, v96
	v_mov_b32_e32 v33, v96
	v_mov_b32_e32 v34, v96
	v_mov_b32_e32 v35, v96
	v_mov_b32_e32 v36, v96
	v_mov_b32_e32 v37, v96
	v_mov_b32_e32 v38, v96
	v_mov_b32_e32 v39, v96
	v_mov_b32_e32 v40, v96
	v_mov_b32_e32 v41, v96
	v_mov_b32_e32 v42, v96
	v_mov_b32_e32 v43, v96
	v_mov_b32_e32 v44, v96
	v_mov_b32_e32 v45, v96
	v_mov_b32_e32 v46, v96
	v_mov_b32_e32 v47, v96
	v_mov_b32_e32 v48, v96
	v_mov_b32_e32 v49, v96
	v_mov_b32_e32 v50, v96
	v_mov_b32_e32 v51, v96
	v_mov_b32_e32 v52, v96
	v_mov_b32_e32 v53, v96
	v_mov_b32_e32 v54, v96
	v_mov_b32_e32 v55, v96
	v_mov_b32_e32 v60, v96
	v_mov_b32_e32 v61, v96
	v_mov_b32_e32 v62, v96
	v_mov_b32_e32 v63, v96
	v_mov_b32_e32 v68, v96
	v_mov_b32_e32 v69, v96
	v_mov_b32_e32 v70, v96
	v_mov_b32_e32 v71, v96
	v_mov_b32_e32 v0, v96
	v_mov_b32_e32 v1, v96
	v_mov_b32_e32 v2, v96
	v_mov_b32_e32 v3, v96
	v_mov_b32_e32 v4, v96
	v_mov_b32_e32 v5, v96
	v_mov_b32_e32 v6, v96
	v_mov_b32_e32 v7, v96
	v_mov_b32_e32 v8, v96
	v_mov_b32_e32 v9, v96
	v_mov_b32_e32 v10, v96
	v_mov_b32_e32 v11, v96
	v_mov_b32_e32 v12, v96
	v_mov_b32_e32 v13, v96
	v_mov_b32_e32 v14, v96
	v_mov_b32_e32 v15, v96
	v_mov_b32_e32 v16, v96
	v_mov_b32_e32 v17, v96
	v_mov_b32_e32 v18, v96
	v_mov_b32_e32 v19, v96
	v_mov_b32_e32 v20, v96
	v_mov_b32_e32 v21, v96
	v_mov_b32_e32 v22, v96
	v_mov_b32_e32 v23, v96
	v_mov_b32_e32 v24, v96
	v_mov_b32_e32 v25, v96
	v_mov_b32_e32 v26, v96
	v_mov_b32_e32 v27, v96
	v_mov_b32_e32 v28, v96
	v_mov_b32_e32 v29, v96
	v_mov_b32_e32 v30, v96
	v_mov_b32_e32 v31, v96

; #define MMA(ai,bj,Af,Bf) do{__builtin_amdgcn_s_setprio(1); \
;     _Pragma("unroll") for(int m=0;m<4;++m) _Pragma("unroll") for(int n=0;n<2;++n) _Pragma("unroll") for(int k=0;k<2;++k) \
;       acc[ai][bj][m][n]=__builtin_amdgcn_mfma_f32_16x16x32_bf16(Bf[n][k],Af[m][k],acc[ai][bj][m][n],0,0,0); \
;     __builtin_amdgcn_s_setprio(0);}while(0)
; #define WAIT_V(n) asm volatile("s_waitcnt vmcnt(" #n ")":::"memory")
; #define BAR __builtin_amdgcn_s_barrier()
; #define STAGE_B(b,h,kt) do{ unsigned char* _d = SB(b,h) + wbase; \
;     if constexpr (BLK) { const char* _s = ((h)?baseB1:baseB0) + (size_t)(kt) * 16384; GLDS(_s + voa, _d); GLDS(_s + 8192 + voa, _d + 8192); } \
;     else { const char* _s = ((h)?baseB1:baseB0) + (kt)*128; GLDS(_s + voa, _d); GLDS(_s + (size_t)128*K + voa, _d + 8192); } }while(0)
; template <int K, int EPI, bool MIX = false>
; __device__ __forceinline__ void gemm_phase(const Params& p, const u16* __restrict__ A, const u16* __restrict__ Bt,
;                            const float* __restrict__ rs_in, float* __restrict__ ssq_out, float alpha, bool rev = false) {
;     ...
;       if (more) { STAGE_B(1,1,1); WAIT_V(6); }
;       BAR; MMA(1,1,At,B1); BAR;
;       if (!more && wr == 0) BAR;
.LBB0_202:
	s_barrier
	s_setprio 1
	v_mfma_f32_16x16x32_bf16 v[8:11], v[128:131], v[164:167], v[8:11]
	v_mfma_f32_16x16x32_bf16 v[44:47], v[196:199], v[168:171], v[8:11]
	v_mfma_f32_16x16x32_bf16 v[8:11], v[132:135], v[164:167], v[12:15]
	v_mfma_f32_16x16x32_bf16 v[24:27], v[128:131], v[56:59], v[140:143]
	v_mfma_f32_16x16x32_bf16 v[40:43], v[192:195], v[168:171], v[8:11]
	v_mfma_f32_16x16x32_bf16 v[8:11], v[128:131], v[160:163], v[148:151]
	v_mfma_f32_16x16x32_bf16 v[60:63], v[196:199], v[204:207], v[24:27]
	v_mfma_f32_16x16x32_bf16 v[24:27], v[132:135], v[56:59], v[144:147]
	v_mfma_f32_16x16x32_bf16 v[28:31], v[196:199], v[200:203], v[8:11]
	v_mfma_f32_16x16x32_bf16 v[8:11], v[132:135], v[160:163], v[180:183]
	v_mfma_f32_16x16x32_bf16 v[56:59], v[192:195], v[204:207], v[24:27]
	v_mfma_f32_16x16x32_bf16 v[24:27], v[192:195], v[200:203], v[8:11]
	v_mfma_f32_16x16x32_bf16 v[8:11], v[128:131], v[152:155], v[184:187]
	v_mfma_f32_16x16x32_bf16 v[12:15], v[196:199], v[156:159], v[8:11]
	v_mfma_f32_16x16x32_bf16 v[8:11], v[132:135], v[152:155], v[188:191]
	v_mfma_f32_16x16x32_bf16 v[8:11], v[192:195], v[156:159], v[8:11]
	s_setprio 0
	v_readlane_b32 vcc_lo, v255, 18
	v_readlane_b32 vcc_hi, v255, 19
	s_nop 3
	s_or_b64 vcc, vcc, s[10:11]
	s_cbranch_scc0 .Llate_p3_defer
	s_barrier
.Llate_p3_defer:
	s_andn2_b64 vcc, exec, s[4:5]
	s_cbranch_vccnz .LBB0_204
	s_barrier

; #define SCHED __builtin_amdgcn_sched_barrier(0)
; template <int K, int EPI, bool MIX = false>
; __device__ __forceinline__ void gemm_phase(const Params& p, const u16* __restrict__ A, const u16* __restrict__ Bt,
;                            const float* __restrict__ rs_in, float* __restrict__ ssq_out, float alpha, bool rev = false) {
;     ...
;   for (;;) {
;     f32x4 acc[2][2][4][2];
; #pragma unroll
;     for (int a = 0; a < 2; ++a)
; #pragma unroll
;       for (int b = 0; b < 2; ++b)
; #pragma unroll
;         for (int m = 0; m < 4; ++m)
; #pragma unroll
;           for (int n = 0; n < 2; ++n) acc[a][b][m][n] = f32x4{0.f, 0.f, 0.f, 0.f};
;     bf16x8 At[4][2], B0[2][2], B1[2][2];
;     asm volatile("" ::: "memory");
;     SCHED;
.LBB0_363:
	s_andn2_b64 vcc, exec, s[4:5]
	s_cbranch_vccz .LBB0_406
	s_and_b64 vcc, exec, s[26:27]
	s_cbranch_vccnz .Llate_p5_done
	s_barrier
.Llate_p5_done:
.LBB0_364:
	s_mov_b32 s78, s33
	v_mov_b32_e32 v0, 0
	s_mov_b32 s33, -2
	s_mov_b64 s[4:5], s[16:17]
	s_mov_b64 s[6:7], s[8:9]
	s_mov_b64 s[60:61], s[12:13]
	s_waitcnt lgkmcnt(0)
	v_mov_b32_e32 v1, v0
	v_mov_b32_e32 v2, v0
	v_mov_b32_e32 v3, v0
	v_mov_b32_e32 v4, v0
	v_mov_b32_e32 v5, v0
	v_mov_b32_e32 v6, v0
	v_mov_b32_e32 v7, v0
	v_mov_b32_e32 v56, v0
	v_mov_b32_e32 v57, v0
	v_mov_b32_e32 v58, v0
	v_mov_b32_e32 v59, v0
	v_mov_b32_e32 v60, v0
	v_mov_b32_e32 v61, v0
	v_mov_b32_e32 v62, v0
	v_mov_b32_e32 v63, v0
	v_mov_b32_e32 v104, v0
	v_mov_b32_e32 v105, v0
	v_mov_b32_e32 v106, v0
	v_mov_b32_e32 v107, v0
	v_mov_b32_e32 v108, v0
	v_mov_b32_e32 v109, v0
	v_mov_b32_e32 v110, v0
	v_mov_b32_e32 v111, v0
	v_mov_b32_e32 v80, v0
	v_mov_b32_e32 v81, v0
	v_mov_b32_e32 v82, v0
	v_mov_b32_e32 v83, v0
	v_mov_b32_e32 v84, v0
	v_mov_b32_e32 v85, v0
	v_mov_b32_e32 v86, v0
	v_mov_b32_e32 v87, v0
	v_mov_b32_e32 v72, v0
	v_mov_b32_e32 v73, v0
	v_mov_b32_e32 v74, v0
	v_mov_b32_e32 v75, v0
	v_mov_b32_e32 v76, v0
	v_mov_b32_e32 v77, v0
	v_mov_b32_e32 v78, v0
	v_mov_b32_e32 v79, v0
	v_mov_b32_e32 v48, v0
	v_mov_b32_e32 v49, v0
	v_mov_b32_e32 v50, v0
	v_mov_b32_e32 v51, v0
	v_mov_b32_e32 v52, v0
	v_mov_b32_e32 v53, v0
	v_mov_b32_e32 v54, v0
	v_mov_b32_e32 v55, v0
	v_mov_b32_e32 v32, v0
	v_mov_b32_e32 v33, v0
	v_mov_b32_e32 v34, v0
	v_mov_b32_e32 v35, v0
	v_mov_b32_e32 v36, v0
	v_mov_b32_e32 v37, v0
	v_mov_b32_e32 v38, v0
	v_mov_b32_e32 v39, v0
	v_mov_b32_e32 v16, v0
	v_mov_b32_e32 v17, v0
	v_mov_b32_e32 v18, v0
	v_mov_b32_e32 v19, v0
	v_mov_b32_e32 v20, v0
	v_mov_b32_e32 v21, v0
	v_mov_b32_e32 v22, v0
	v_mov_b32_e32 v23, v0
	v_mov_b32_e32 v96, v0
	v_mov_b32_e32 v97, v0
	v_mov_b32_e32 v98, v0
	v_mov_b32_e32 v99, v0
	v_mov_b32_e32 v100, v0
	v_mov_b32_e32 v101, v0
	v_mov_b32_e32 v102, v0
	v_mov_b32_e32 v103, v0
	v_mov_b32_e32 v64, v0
	v_mov_b32_e32 v65, v0
	v_mov_b32_e32 v66, v0
	v_mov_b32_e32 v67, v0
	v_mov_b32_e32 v68, v0
	v_mov_b32_e32 v69, v0
	v_mov_b32_e32 v70, v0
	v_mov_b32_e32 v71, v0
	v_mov_b32_e32 v40, v0
	v_mov_b32_e32 v41, v0
	v_mov_b32_e32 v42, v0
	v_mov_b32_e32 v43, v0
	v_mov_b32_e32 v44, v0
	v_mov_b32_e32 v45, v0
	v_mov_b32_e32 v46, v0
	v_mov_b32_e32 v47, v0
	v_mov_b32_e32 v24, v0
	v_mov_b32_e32 v25, v0
	v_mov_b32_e32 v26, v0
	v_mov_b32_e32 v27, v0
	v_mov_b32_e32 v28, v0
	v_mov_b32_e32 v29, v0
	v_mov_b32_e32 v30, v0
	v_mov_b32_e32 v31, v0
	v_mov_b32_e32 v128, v0
	v_mov_b32_e32 v129, v0
	v_mov_b32_e32 v130, v0
	v_mov_b32_e32 v131, v0
	v_mov_b32_e32 v132, v0
	v_mov_b32_e32 v133, v0
	v_mov_b32_e32 v134, v0
	v_mov_b32_e32 v135, v0
	v_mov_b32_e32 v120, v0
	v_mov_b32_e32 v121, v0
	v_mov_b32_e32 v122, v0
	v_mov_b32_e32 v123, v0
	v_mov_b32_e32 v124, v0
	v_mov_b32_e32 v125, v0
	v_mov_b32_e32 v126, v0
	v_mov_b32_e32 v127, v0
	v_mov_b32_e32 v88, v0
	v_mov_b32_e32 v89, v0
	v_mov_b32_e32 v90, v0
	v_mov_b32_e32 v91, v0
	v_mov_b32_e32 v92, v0
	v_mov_b32_e32 v93, v0
	v_mov_b32_e32 v94, v0
	v_mov_b32_e32 v95, v0
	v_mov_b32_e32 v12, v0
	v_mov_b32_e32 v13, v0
	v_mov_b32_e32 v14, v0
	v_mov_b32_e32 v15, v0
	v_mov_b32_e32 v8, v0
	v_mov_b32_e32 v9, v0
	v_mov_b32_e32 v10, v0
	v_mov_b32_e32 v11, v0

; #define MMA(ai,bj,Af,Bf) do{__builtin_amdgcn_s_setprio(1); \
;     _Pragma("unroll") for(int m=0;m<4;++m) _Pragma("unroll") for(int n=0;n<2;++n) _Pragma("unroll") for(int k=0;k<2;++k) \
;       acc[ai][bj][m][n]=__builtin_amdgcn_mfma_f32_16x16x32_bf16(Bf[n][k],Af[m][k],acc[ai][bj][m][n],0,0,0); \
;     __builtin_amdgcn_s_setprio(0);}while(0)
; #define WAIT_V(n) asm volatile("s_waitcnt vmcnt(" #n ")":::"memory")
; #define BAR __builtin_amdgcn_s_barrier()
; #define STAGE_B(b,h,kt) do{ unsigned char* _d = SB(b,h) + wbase; \
;     if constexpr (BLK) { const char* _s = ((h)?baseB1:baseB0) + (size_t)(kt) * 16384; GLDS(_s + voa, _d); GLDS(_s + 8192 + voa, _d + 8192); } \
;     else { const char* _s = ((h)?baseB1:baseB0) + (kt)*128; GLDS(_s + voa, _d); GLDS(_s + (size_t)128*K + voa, _d + 8192); } }while(0)
; template <int K, int EPI, bool MIX = false>
; __device__ __forceinline__ void gemm_phase(const Params& p, const u16* __restrict__ A, const u16* __restrict__ Bt,
;                            const float* __restrict__ rs_in, float* __restrict__ ssq_out, float alpha, bool rev = false) {
;     ...
;       if (more) { STAGE_B(1,1,1); WAIT_V(6); }
;       BAR; MMA(1,1,At,B1); BAR;
;       if (!more && wr == 0) BAR;
.LBB0_386:
	s_barrier
	s_setprio 1
	v_mfma_f32_16x16x32_bf16 v[52:55], v[8:11], v[36:39], v[144:147]
	v_mfma_f32_16x16x32_bf16 v[36:39], v[208:211], v[36:39], v[148:151]
	v_mfma_f32_16x16x32_bf16 v[52:55], v[12:15], v[48:51], v[52:55]
	v_mfma_f32_16x16x32_bf16 v[48:51], v[212:215], v[48:51], v[36:39]
	v_mfma_f32_16x16x32_bf16 v[36:39], v[8:11], v[20:23], v[176:179]
	v_mfma_f32_16x16x32_bf16 v[20:23], v[208:211], v[20:23], v[180:183]
	v_mfma_f32_16x16x32_bf16 v[36:39], v[12:15], v[32:35], v[36:39]
	v_mfma_f32_16x16x32_bf16 v[32:35], v[212:215], v[32:35], v[20:23]
	v_mfma_f32_16x16x32_bf16 v[20:23], v[8:11], v[16:19], v[184:187]
	v_mfma_f32_16x16x32_bf16 v[8:11], v[8:11], v[152:155], v[192:195]
	v_mfma_f32_16x16x32_bf16 v[20:23], v[12:15], v[216:219], v[20:23]
	v_mfma_f32_16x16x32_bf16 v[16:19], v[208:211], v[16:19], v[188:191]
	v_mfma_f32_16x16x32_bf16 v[12:15], v[12:15], v[156:159], v[8:11]
	v_mfma_f32_16x16x32_bf16 v[8:11], v[208:211], v[152:155], v[196:199]
	v_mfma_f32_16x16x32_bf16 v[16:19], v[212:215], v[216:219], v[16:19]
	v_mfma_f32_16x16x32_bf16 v[8:11], v[212:215], v[156:159], v[8:11]
	s_setprio 0
	s_or_b64 vcc, s[4:5], s[26:27]
	s_cbranch_scc0 .Llate_p5_defer
	s_barrier
.Llate_p5_defer:
	s_andn2_b64 vcc, exec, s[6:7]
	s_cbranch_vccnz .LBB0_388
	s_barrier

; #define SCHED __builtin_amdgcn_sched_barrier(0)
; template <int K, int EPI, bool MIX = false>
; __device__ __forceinline__ void gemm_phase(const Params& p, const u16* __restrict__ A, const u16* __restrict__ Bt,
;                            const float* __restrict__ rs_in, float* __restrict__ ssq_out, float alpha, bool rev = false) {
;     ...
;   for (;;) {
;     f32x4 acc[2][2][4][2];
; #pragma unroll
;     for (int a = 0; a < 2; ++a)
; #pragma unroll
;       for (int b = 0; b < 2; ++b)
; #pragma unroll
;         for (int m = 0; m < 4; ++m)
; #pragma unroll
;           for (int n = 0; n < 2; ++n) acc[a][b][m][n] = f32x4{0.f, 0.f, 0.f, 0.f};
;     bf16x8 At[4][2], B0[2][2], B1[2][2];
;     asm volatile("" ::: "memory");
;     SCHED;
.LBB0_421:
	s_andn2_b64 vcc, exec, s[4:5]
	s_cbranch_vccz .LBB0_446
	s_and_b64 vcc, exec, s[20:21]
	s_cbranch_vccnz .Llate_p6_done
	s_barrier
.Llate_p6_done:
.LBB0_422:
	s_mov_b32 s76, s58
	v_mov_b32_e32 v0, 0
	s_mov_b32 s77, -2
	s_mov_b64 s[4:5], s[10:11]
	s_mov_b64 s[52:53], s[0:1]
	s_mov_b64 s[58:59], s[8:9]
	v_mov_b32_e32 v1, v0
	v_mov_b32_e32 v2, v0
	v_mov_b32_e32 v3, v0
	v_mov_b32_e32 v4, v0
	v_mov_b32_e32 v5, v0
	v_mov_b32_e32 v6, v0
	v_mov_b32_e32 v7, v0
	v_mov_b32_e32 v8, v0
	v_mov_b32_e32 v9, v0
	v_mov_b32_e32 v10, v0
	v_mov_b32_e32 v11, v0
	v_mov_b32_e32 v12, v0
	v_mov_b32_e32 v13, v0
	v_mov_b32_e32 v14, v0
	v_mov_b32_e32 v15, v0
	v_mov_b32_e32 v16, v0
	v_mov_b32_e32 v17, v0
	v_mov_b32_e32 v18, v0
	v_mov_b32_e32 v19, v0
	v_mov_b32_e32 v20, v0
	v_mov_b32_e32 v21, v0
	v_mov_b32_e32 v22, v0
	v_mov_b32_e32 v23, v0
	v_mov_b32_e32 v24, v0
	v_mov_b32_e32 v25, v0
	v_mov_b32_e32 v26, v0
	v_mov_b32_e32 v27, v0
	v_mov_b32_e32 v28, v0
	v_mov_b32_e32 v29, v0
	v_mov_b32_e32 v30, v0
	v_mov_b32_e32 v31, v0
	v_mov_b32_e32 v64, v0
	v_mov_b32_e32 v65, v0
	v_mov_b32_e32 v66, v0
	v_mov_b32_e32 v67, v0
	v_mov_b32_e32 v68, v0
	v_mov_b32_e32 v69, v0
	v_mov_b32_e32 v70, v0
	v_mov_b32_e32 v71, v0
	v_mov_b32_e32 v72, v0
	v_mov_b32_e32 v73, v0
	v_mov_b32_e32 v74, v0
	v_mov_b32_e32 v75, v0
	v_mov_b32_e32 v76, v0
	v_mov_b32_e32 v77, v0
	v_mov_b32_e32 v78, v0
	v_mov_b32_e32 v79, v0
	v_mov_b32_e32 v80, v0
	v_mov_b32_e32 v81, v0
	v_mov_b32_e32 v82, v0
	v_mov_b32_e32 v83, v0
	v_mov_b32_e32 v84, v0
	v_mov_b32_e32 v85, v0
	v_mov_b32_e32 v86, v0
	v_mov_b32_e32 v87, v0
	v_mov_b32_e32 v88, v0
	v_mov_b32_e32 v89, v0
	v_mov_b32_e32 v90, v0
	v_mov_b32_e32 v91, v0
	v_mov_b32_e32 v92, v0
	v_mov_b32_e32 v93, v0
	v_mov_b32_e32 v94, v0
	v_mov_b32_e32 v95, v0
	v_mov_b32_e32 v96, v0
	v_mov_b32_e32 v97, v0
	v_mov_b32_e32 v98, v0
	v_mov_b32_e32 v99, v0
	v_mov_b32_e32 v100, v0
	v_mov_b32_e32 v101, v0
	v_mov_b32_e32 v102, v0
	v_mov_b32_e32 v103, v0
	v_mov_b32_e32 v104, v0
	v_mov_b32_e32 v105, v0
	v_mov_b32_e32 v106, v0
	v_mov_b32_e32 v107, v0
	v_mov_b32_e32 v108, v0
	v_mov_b32_e32 v109, v0
	v_mov_b32_e32 v110, v0
	v_mov_b32_e32 v111, v0
	v_mov_b32_e32 v112, v0
	v_mov_b32_e32 v113, v0
	v_mov_b32_e32 v114, v0
	v_mov_b32_e32 v115, v0
	v_mov_b32_e32 v116, v0
	v_mov_b32_e32 v117, v0
	v_mov_b32_e32 v118, v0
	v_mov_b32_e32 v119, v0
	v_mov_b32_e32 v120, v0
	v_mov_b32_e32 v121, v0
	v_mov_b32_e32 v122, v0
	v_mov_b32_e32 v123, v0
	v_mov_b32_e32 v124, v0
	v_mov_b32_e32 v125, v0
	v_mov_b32_e32 v126, v0
	v_mov_b32_e32 v127, v0
	v_mov_b32_e32 v32, v0
	v_mov_b32_e32 v33, v0
	v_mov_b32_e32 v34, v0
	v_mov_b32_e32 v35, v0
	v_mov_b32_e32 v36, v0
	v_mov_b32_e32 v37, v0
	v_mov_b32_e32 v38, v0
	v_mov_b32_e32 v39, v0
	v_mov_b32_e32 v40, v0
	v_mov_b32_e32 v41, v0
	v_mov_b32_e32 v42, v0
	v_mov_b32_e32 v43, v0
	v_mov_b32_e32 v44, v0
	v_mov_b32_e32 v45, v0
	v_mov_b32_e32 v46, v0
	v_mov_b32_e32 v47, v0
	v_mov_b32_e32 v48, v0
	v_mov_b32_e32 v49, v0
	v_mov_b32_e32 v50, v0
	v_mov_b32_e32 v51, v0
	v_mov_b32_e32 v52, v0
	v_mov_b32_e32 v53, v0
	v_mov_b32_e32 v54, v0
	v_mov_b32_e32 v55, v0
	v_mov_b32_e32 v56, v0
	v_mov_b32_e32 v57, v0
	v_mov_b32_e32 v58, v0
	v_mov_b32_e32 v59, v0
	v_mov_b32_e32 v60, v0
	v_mov_b32_e32 v61, v0
	v_mov_b32_e32 v62, v0
	v_mov_b32_e32 v63, v0

; #define MMA(ai,bj,Af,Bf) do{__builtin_amdgcn_s_setprio(1); \
;     _Pragma("unroll") for(int m=0;m<4;++m) _Pragma("unroll") for(int n=0;n<2;++n) _Pragma("unroll") for(int k=0;k<2;++k) \
;       acc[ai][bj][m][n]=__builtin_amdgcn_mfma_f32_16x16x32_bf16(Bf[n][k],Af[m][k],acc[ai][bj][m][n],0,0,0); \
;     __builtin_amdgcn_s_setprio(0);}while(0)
; #define WAIT_V(n) asm volatile("s_waitcnt vmcnt(" #n ")":::"memory")
; #define BAR __builtin_amdgcn_s_barrier()
; #define STAGE_B(b,h,kt) do{ unsigned char* _d = SB(b,h) + wbase; \
;     if constexpr (BLK) { const char* _s = ((h)?baseB1:baseB0) + (size_t)(kt) * 16384; GLDS(_s + voa, _d); GLDS(_s + 8192 + voa, _d + 8192); } \
;     else { const char* _s = ((h)?baseB1:baseB0) + (kt)*128; GLDS(_s + voa, _d); GLDS(_s + (size_t)128*K + voa, _d + 8192); } }while(0)
; template <int K, int EPI, bool MIX = false>
; __device__ __forceinline__ void gemm_phase(const Params& p, const u16* __restrict__ A, const u16* __restrict__ Bt,
;                            const float* __restrict__ rs_in, float* __restrict__ ssq_out, float alpha, bool rev = false) {
;     ...
;       if (more) { STAGE_B(1,1,1); WAIT_V(6); }
;       BAR; MMA(1,1,At,B1); BAR;
;       if (!more && wr == 0) BAR;
;     ...
;     if constexpr (EPI == EPI_SWIGLU) {
; #pragma unroll
;       for (int ai = 0; ai < 2; ++ai)
; #pragma unroll
;         for (int m = 0; m < 4; ++m) {
;           int row = brow + ai * 128 + wr * 64 + m * 16 + fr_e;
;           const float rs = rsqrtf(rsq[ai][m] * (1.f / DM) + 1e-6f);
;           const float c1 = rs * -1.4426950408889634f, rs2 = rs * rs;
;           u16* orow = p.Bbuf + blk_off(row, cpn * 128 + wc * 32, DFF) + wn16;
;           uint2 o2[2];
; #pragma unroll
;           for (int n = 0; n < 2; ++n) {
;             f32x4 g = acc[ai][0][m][n], u = acc[ai][1][m][n];
;             float h[4];
; #pragma unroll
;             for (int j = 0; j < 4; ++j) h[j] = (g[j] * u[j]) * (rs2 * __builtin_amdgcn_rcpf(1.f + __builtin_amdgcn_exp2f(g[j] * c1)));
;             o2[n].x = pk2(h[0], h[1]); o2[n].y = pk2(h[2], h[3]);
;           }
;           *(uint4*)orow = widen_pair(o2[0], o2[1]);
;         }
.LBB0_442:
	s_barrier
	s_setprio 1
	v_mfma_f32_16x16x32_bf16 v[4:7], v[128:131], v[204:207], v[136:139]
	v_mfma_f32_16x16x32_bf16 v[64:67], v[188:191], v[208:211], v[4:7]
	v_mfma_f32_16x16x32_bf16 v[4:7], v[132:135], v[204:207], v[36:39]
	v_mfma_f32_16x16x32_bf16 v[52:55], v[184:187], v[208:211], v[4:7]
	v_mfma_f32_16x16x32_bf16 v[4:7], v[128:131], v[192:195], v[140:143]
	v_mfma_f32_16x16x32_bf16 v[44:47], v[188:191], v[196:199], v[4:7]
	v_mfma_f32_16x16x32_bf16 v[4:7], v[132:135], v[192:195], v[144:147]
	v_mfma_f32_16x16x32_bf16 v[36:39], v[184:187], v[196:199], v[4:7]
	v_mfma_f32_16x16x32_bf16 v[4:7], v[128:131], v[160:163], v[148:151]
	v_mfma_f32_16x16x32_bf16 v[28:31], v[188:191], v[200:203], v[4:7]
	v_mfma_f32_16x16x32_bf16 v[4:7], v[132:135], v[160:163], v[164:167]
	v_mfma_f32_16x16x32_bf16 v[20:23], v[184:187], v[200:203], v[4:7]
	v_mfma_f32_16x16x32_bf16 v[4:7], v[128:131], v[152:155], v[168:171]
	v_mfma_f32_16x16x32_bf16 v[12:15], v[188:191], v[156:159], v[4:7]
	v_mfma_f32_16x16x32_bf16 v[4:7], v[132:135], v[152:155], v[172:175]
	v_mfma_f32_16x16x32_bf16 v[4:7], v[184:187], v[156:159], v[4:7]
	s_setprio 0
	s_or_b64 vcc, s[4:5], s[20:21]
	s_cbranch_scc0 .Llate_p6_defer
	s_barrier
.Llate_p6_defer:
	s_andn2_b64 vcc, exec, s[52:53]
	s_cbranch_vccnz .LBB0_444
	s_barrier
.LBB0_444:
	v_mov_b32_e32 v129, v222
	v_pk_mul_f32 v[118:119], v[126:127], v[118:119]
	v_lshrrev_b32_e32 v130, 1, v129
	v_ashrrev_i32_e32 v128, 1, v129
	v_and_b32_e32 v130, 8, v130
	v_and_or_b32 v128, v128, -16, v130
	s_waitcnt vmcnt(6)
	v_fmamk_f32 v130, v214, 0x3a000000, v236
	v_mul_f32_e32 v132, 0x4b800000, v130
	v_cmp_gt_f32_e32 vcc, s74, v130
	v_and_or_b32 v131, v129, 15, s70
	v_lshlrev_b32_e32 v131, 7, v131
	v_cndmask_b32_e32 v130, v130, v132, vcc
	v_rsq_f32_e32 v130, v130
	v_and_b32_e32 v214, 0x2780, v131
	v_pk_mul_f32 v[116:117], v[124:125], v[116:117]
	s_lshl_b32 s52, s76, 7
	v_mul_f32_e32 v132, 0x45800000, v130
	v_cndmask_b32_e32 v130, v130, v132, vcc
	v_mul_f32_e32 v136, 0xbfb8aa3b, v130
	v_mul_f32_e32 v131, v136, v124
	v_exp_f32_e32 v131, v131
	v_mul_f32_e32 v134, v136, v125
	v_exp_f32_e32 v135, v134
	v_mul_f32_e32 v137, v136, v127
	v_add_f32_e32 v131, 1.0, v131
	v_rcp_f32_e32 v134, v131
	v_add_f32_e32 v131, 1.0, v135
	v_rcp_f32_e32 v135, v131
	v_mul_f32_e32 v131, v136, v126
	v_exp_f32_e32 v131, v131
	v_exp_f32_e32 v137, v137
	v_mul_f32_e32 v130, v130, v130
	s_or_b32 s52, s52, s71
	v_add_f32_e32 v126, 1.0, v131
	v_add_f32_e32 v127, 1.0, v137
	v_rcp_f32_e32 v126, v126
	v_rcp_f32_e32 v127, v127
	v_pk_mul_f32 v[124:125], v[130:131], v[134:135] op_sel_hi:[0,1]
	v_pk_mul_f32 v[116:117], v[124:125], v[116:117]
	s_ashr_i32 s76, s52, 6
	v_pk_mul_f32 v[124:125], v[130:131], v[126:127] op_sel_hi:[0,1]
	v_cvt_pk_bf16_f32 v116, v116, v117
	v_mul_f32_e32 v117, v136, v120
	v_pk_mul_f32 v[118:119], v[124:125], v[118:119]
	v_exp_f32_e32 v124, v117
	v_mul_f32_e32 v117, v136, v121
	v_exp_f32_e32 v125, v117
	v_cvt_pk_bf16_f32 v117, v118, v119
	v_add_f32_e32 v118, 1.0, v124
	v_mul_f32_e32 v124, v136, v122
	v_add_f32_e32 v119, 1.0, v125
	v_mul_f32_e32 v125, v136, v123
	v_exp_f32_e32 v124, v124
	v_exp_f32_e32 v125, v125
	s_ashr_i32 s52, s59, 7
	s_mulk_i32 s52, 0x58
	s_ashr_i32 s77, s76, 31
	s_ashr_i32 s53, s52, 31
	v_rcp_f32_e32 v118, v118
	v_rcp_f32_e32 v119, v119
	v_pk_mul_f32 v[114:115], v[122:123], v[114:115]
	v_add_f32_e32 v122, 1.0, v124
	v_add_f32_e32 v123, 1.0, v125
	s_add_u32 s52, s52, s76
	v_rcp_f32_e32 v122, v122
	v_rcp_f32_e32 v123, v123
	s_addc_u32 s53, s53, s77
	v_pk_mul_f32 v[112:113], v[120:121], v[112:113]
	v_fmamk_f32 v120, v243, 0x3a000000, v236
	s_lshl_b64 s[52:53], s[52:53], 14
	v_mul_f32_e32 v121, 0x4b800000, v120
	v_cmp_gt_f32_e32 vcc, s74, v120
	s_add_u32 s52, s92, s52
	v_pk_mul_f32 v[118:119], v[130:131], v[118:119] op_sel_hi:[0,1]
	v_cndmask_b32_e32 v120, v120, v121, vcc
	s_addc_u32 s53, s93, s53
	v_pk_mul_f32 v[112:113], v[118:119], v[112:113]
	v_pk_mul_f32 v[118:119], v[130:131], v[122:123] op_sel_hi:[0,1]
	v_rsq_f32_e32 v120, v120
	v_ashrrev_i32_e32 v129, 31, v128
	v_lshl_add_u64 v[132:133], s[52:53], 0, v[214:215]
	v_pk_mul_f32 v[114:115], v[118:119], v[114:115]
	v_lshl_add_u64 v[132:133], v[132:133], 0, s[22:23]
	v_cvt_pk_bf16_f32 v118, v112, v113
	v_cvt_pk_bf16_f32 v119, v114, v115
	v_lshlrev_b64 v[112:113], 1, v[128:129]
	v_lshl_add_u64 v[114:115], v[132:133], 0, v[112:113]
	v_permlane32_swap_b32_e32 v116, v118
	v_permlane32_swap_b32_e32 v117, v119
	global_store_dwordx4 v[114:115], v[116:119], off
	s_addk_i32 s59, 0x80
	s_nop 0
	v_mul_f32_e32 v116, 0x45800000, v120
	v_cndmask_b32_e32 v116, v120, v116, vcc
	v_mul_f32_e32 v117, 0xbfb8aa3b, v116
	v_mul_f32_e32 v118, v117, v100
	v_mul_f32_e32 v119, v117, v101
	v_exp_f32_e32 v118, v118
	v_exp_f32_e32 v119, v119
	v_mul_f32_e32 v120, v117, v102
	v_mul_f32_e32 v121, v117, v103
	v_exp_f32_e32 v120, v120
	v_exp_f32_e32 v121, v121
	v_add_f32_e32 v118, 1.0, v118
	v_add_f32_e32 v119, 1.0, v119
	v_rcp_f32_e32 v118, v118
	v_rcp_f32_e32 v119, v119
	v_pk_mul_f32 v[102:103], v[102:103], v[110:111]
	v_add_f32_e32 v110, 1.0, v120
	v_add_f32_e32 v111, 1.0, v121
	v_rcp_f32_e32 v110, v110
	v_rcp_f32_e32 v111, v111
	v_mul_f32_e32 v116, v116, v116
	v_pk_mul_f32 v[100:101], v[100:101], v[108:109]
	v_pk_mul_f32 v[108:109], v[116:117], v[118:119] op_sel_hi:[0,1]
	v_pk_mul_f32 v[100:101], v[108:109], v[100:101]
	v_pk_mul_f32 v[108:109], v[116:117], v[110:111] op_sel_hi:[0,1]
	v_cvt_pk_bf16_f32 v100, v100, v101
	v_mul_f32_e32 v101, v117, v96
	v_pk_mul_f32 v[102:103], v[108:109], v[102:103]
	v_exp_f32_e32 v108, v101
	v_mul_f32_e32 v101, v117, v97
	v_exp_f32_e32 v109, v101
	v_cvt_pk_bf16_f32 v101, v102, v103
; template <int K, int EPI, bool MIX = false>
; __device__ __forceinline__ void gemm_phase(const Params& p, const u16* __restrict__ A, const u16* __restrict__ Bt,
;                            const float* __restrict__ rs_in, float* __restrict__ ssq_out, float alpha, bool rev = false) {
;     ...
;     if constexpr (EPI == EPI_SWIGLU) {
; #pragma unroll
;       for (int ai = 0; ai < 2; ++ai)
; #pragma unroll
;         for (int m = 0; m < 4; ++m) {
;           int row = brow + ai * 128 + wr * 64 + m * 16 + fr_e;
;           const float rs = rsqrtf(rsq[ai][m] * (1.f / DM) + 1e-6f);
;           const float c1 = rs * -1.4426950408889634f, rs2 = rs * rs;
;           u16* orow = p.Bbuf + blk_off(row, cpn * 128 + wc * 32, DFF) + wn16;
;           uint2 o2[2];
; #pragma unroll
;           for (int n = 0; n < 2; ++n) {
;             f32x4 g = acc[ai][0][m][n], u = acc[ai][1][m][n];
;             float h[4];
; #pragma unroll
;             for (int j = 0; j < 4; ++j) h[j] = (g[j] * u[j]) * (rs2 * __builtin_amdgcn_rcpf(1.f + __builtin_amdgcn_exp2f(g[j] * c1)));
;             o2[n].x = pk2(h[0], h[1]); o2[n].y = pk2(h[2], h[3]);
;           }
;           *(uint4*)orow = widen_pair(o2[0], o2[1]);
;         }
	v_add_f32_e32 v102, 1.0, v108
	v_mul_f32_e32 v108, v117, v98
	v_add_f32_e32 v103, 1.0, v109
	v_mul_f32_e32 v109, v117, v99
	v_exp_f32_e32 v108, v108
	v_exp_f32_e32 v109, v109
	v_rcp_f32_e32 v102, v102
	v_rcp_f32_e32 v103, v103
	v_pk_mul_f32 v[98:99], v[98:99], v[106:107]
	v_add_f32_e32 v106, 1.0, v108
	v_add_f32_e32 v107, 1.0, v109
	v_rcp_f32_e32 v106, v106
	v_rcp_f32_e32 v107, v107
	v_pk_mul_f32 v[96:97], v[96:97], v[104:105]
	v_pk_mul_f32 v[102:103], v[116:117], v[102:103] op_sel_hi:[0,1]
	v_pk_mul_f32 v[96:97], v[102:103], v[96:97]
	v_pk_mul_f32 v[102:103], v[116:117], v[106:107] op_sel_hi:[0,1]
	v_pk_mul_f32 v[98:99], v[102:103], v[98:99]
	v_cvt_pk_bf16_f32 v102, v96, v97
	v_fmamk_f32 v96, v242, 0x3a000000, v236
	v_mul_f32_e32 v97, 0x4b800000, v96
	v_cmp_gt_f32_e32 vcc, s74, v96
	v_cvt_pk_bf16_f32 v103, v98, v99
	v_permlane32_swap_b32_e32 v100, v102
	v_cndmask_b32_e32 v96, v96, v97, vcc
	v_rsq_f32_e32 v96, v96
	v_permlane32_swap_b32_e32 v101, v103
	global_store_dwordx4 v[114:115], v[100:103], off offset:2048
	v_mul_f32_e32 v97, 0x45800000, v96
	v_cndmask_b32_e32 v96, v96, v97, vcc
	v_mul_f32_e32 v99, 0xbfb8aa3b, v96
	v_mul_f32_e32 v102, v99, v84
	v_mul_f32_e32 v103, v99, v85
	v_exp_f32_e32 v102, v102
	v_exp_f32_e32 v103, v103
	v_mul_f32_e32 v104, v99, v86
	v_mul_f32_e32 v105, v99, v87
	v_exp_f32_e32 v104, v104
	v_exp_f32_e32 v105, v105
	v_add_f32_e32 v102, 1.0, v102
	v_add_f32_e32 v103, 1.0, v103
	v_rcp_f32_e32 v102, v102
	v_rcp_f32_e32 v103, v103
	v_pk_mul_f32 v[86:87], v[86:87], v[94:95]
	v_add_f32_e32 v94, 1.0, v104
	v_add_f32_e32 v95, 1.0, v105
	v_rcp_f32_e32 v94, v94
	v_rcp_f32_e32 v95, v95
	v_mul_f32_e32 v98, v96, v96
	v_pk_mul_f32 v[84:85], v[84:85], v[92:93]
	v_pk_mul_f32 v[92:93], v[98:99], v[102:103] op_sel_hi:[0,1]
	v_pk_mul_f32 v[84:85], v[92:93], v[84:85]
	v_pk_mul_f32 v[92:93], v[98:99], v[94:95] op_sel_hi:[0,1]
	v_cvt_pk_bf16_f32 v84, v84, v85
	v_mul_f32_e32 v85, v99, v80
	v_pk_mul_f32 v[86:87], v[92:93], v[86:87]
	v_exp_f32_e32 v92, v85
	v_mul_f32_e32 v85, v99, v81
	v_exp_f32_e32 v93, v85
	v_cvt_pk_bf16_f32 v85, v86, v87
	v_add_f32_e32 v86, 1.0, v92
	v_mul_f32_e32 v92, v99, v82
	v_add_f32_e32 v87, 1.0, v93
	v_mul_f32_e32 v93, v99, v83
	v_exp_f32_e32 v92, v92
	v_exp_f32_e32 v93, v93
	v_rcp_f32_e32 v86, v86
	v_rcp_f32_e32 v87, v87
	v_pk_mul_f32 v[82:83], v[82:83], v[90:91]
	v_add_f32_e32 v90, 1.0, v92
	v_add_f32_e32 v91, 1.0, v93
	v_rcp_f32_e32 v90, v90
	v_rcp_f32_e32 v91, v91
	v_pk_mul_f32 v[80:81], v[80:81], v[88:89]
	v_pk_mul_f32 v[86:87], v[98:99], v[86:87] op_sel_hi:[0,1]
	v_pk_mul_f32 v[80:81], v[86:87], v[80:81]
	v_pk_mul_f32 v[86:87], v[98:99], v[90:91] op_sel_hi:[0,1]
	v_pk_mul_f32 v[82:83], v[86:87], v[82:83]
	v_or_b32_e32 v96, 0x1000, v214
	v_cvt_pk_bf16_f32 v87, v82, v83
	v_fmamk_f32 v82, v241, 0x3a000000, v236
	v_mul_f32_e32 v83, 0x4b800000, v82
	v_cmp_gt_f32_e32 vcc, s74, v82
	v_mov_b32_e32 v97, v215
	v_lshl_add_u64 v[100:101], s[52:53], 0, v[96:97]
	v_cndmask_b32_e32 v82, v82, v83, vcc
	v_rsq_f32_e32 v82, v82
	v_lshl_add_u64 v[100:101], v[100:101], 0, s[22:23]
	v_cvt_pk_bf16_f32 v86, v80, v81
	v_lshl_add_u64 v[80:81], v[100:101], 0, v[112:113]
	s_nop 0
	v_permlane32_swap_b32_e32 v84, v86
	v_permlane32_swap_b32_e32 v85, v87
	global_store_dwordx4 v[80:81], v[84:87], off
	v_mul_f32_e32 v80, 0x45800000, v82
	v_cndmask_b32_e32 v80, v82, v80, vcc
	v_mul_f32_e32 v83, 0xbfb8aa3b, v80
	v_mul_f32_e32 v86, v83, v68
	v_mul_f32_e32 v87, v83, v69
	v_exp_f32_e32 v86, v86
	v_exp_f32_e32 v87, v87
	v_mul_f32_e32 v88, v83, v70
	v_mul_f32_e32 v89, v83, v71
	v_exp_f32_e32 v88, v88
	v_exp_f32_e32 v89, v89
	v_add_f32_e32 v86, 1.0, v86
	v_add_f32_e32 v87, 1.0, v87
	v_rcp_f32_e32 v86, v86
	v_rcp_f32_e32 v87, v87
	v_pk_mul_f32 v[70:71], v[70:71], v[78:79]
	v_add_f32_e32 v78, 1.0, v88
	v_add_f32_e32 v79, 1.0, v89
	v_rcp_f32_e32 v78, v78
	v_rcp_f32_e32 v79, v79
	v_mul_f32_e32 v82, v80, v80
	v_pk_mul_f32 v[68:69], v[68:69], v[76:77]
	v_pk_mul_f32 v[76:77], v[82:83], v[86:87] op_sel_hi:[0,1]
	v_pk_mul_f32 v[68:69], v[76:77], v[68:69]
	v_pk_mul_f32 v[76:77], v[82:83], v[78:79] op_sel_hi:[0,1]
	v_cvt_pk_bf16_f32 v68, v68, v69
	v_mul_f32_e32 v69, v83, v60
	v_pk_mul_f32 v[70:71], v[76:77], v[70:71]
	v_exp_f32_e32 v76, v69
	v_mul_f32_e32 v69, v83, v61
	v_exp_f32_e32 v77, v69
	v_cvt_pk_bf16_f32 v69, v70, v71
	v_add_f32_e32 v70, 1.0, v76
	v_mul_f32_e32 v76, v83, v62
	v_add_f32_e32 v71, 1.0, v77
	v_mul_f32_e32 v77, v83, v63
	v_exp_f32_e32 v76, v76
	v_exp_f32_e32 v77, v77
	v_rcp_f32_e32 v70, v70
	v_rcp_f32_e32 v71, v71
	v_pk_mul_f32 v[62:63], v[62:63], v[74:75]
	v_add_f32_e32 v74, 1.0, v76
	v_add_f32_e32 v75, 1.0, v77
	v_rcp_f32_e32 v74, v74
	v_rcp_f32_e32 v75, v75
	v_pk_mul_f32 v[60:61], v[60:61], v[72:73]
	v_pk_mul_f32 v[70:71], v[82:83], v[70:71] op_sel_hi:[0,1]
	v_or_b32_e32 v80, 0x1800, v214
	v_mov_b32_e32 v81, v215
	v_pk_mul_f32 v[60:61], v[70:71], v[60:61]
	v_pk_mul_f32 v[70:71], v[82:83], v[74:75] op_sel_hi:[0,1]
	v_lshl_add_u64 v[84:85], s[52:53], 0, v[80:81]
	v_pk_mul_f32 v[62:63], v[70:71], v[62:63]
	v_lshl_add_u64 v[84:85], v[84:85], 0, s[22:23]
	v_cvt_pk_bf16_f32 v70, v60, v61
	v_cvt_pk_bf16_f32 v71, v62, v63
	v_lshl_add_u64 v[60:61], v[84:85], 0, v[112:113]
	v_permlane32_swap_b32_e32 v68, v70
	v_permlane32_swap_b32_e32 v69, v71
	global_store_dwordx4 v[60:61], v[68:71], off
	v_fmamk_f32 v60, v240, 0x3a000000, v236
	v_mul_f32_e32 v61, 0x4b800000, v60
	v_cmp_gt_f32_e32 vcc, s74, v60
	s_ashr_i32 s52, s59, 7
	s_mulk_i32 s52, 0x58
	v_cndmask_b32_e32 v60, v60, v61, vcc
	v_rsq_f32_e32 v60, v60
	s_ashr_i32 s53, s52, 31
	s_add_u32 s52, s52, s76
	s_addc_u32 s53, s53, s77
	v_mul_f32_e32 v61, 0x45800000, v60
	v_cndmask_b32_e32 v60, v60, v61, vcc
; template <int K, int EPI, bool MIX = false>
; __device__ __forceinline__ void gemm_phase(const Params& p, const u16* __restrict__ A, const u16* __restrict__ Bt,
;                            const float* __restrict__ rs_in, float* __restrict__ ssq_out, float alpha, bool rev = false) {
;     ...
;     if constexpr (EPI == EPI_SWIGLU) {
; #pragma unroll
;       for (int ai = 0; ai < 2; ++ai)
; #pragma unroll
;         for (int m = 0; m < 4; ++m) {
;           int row = brow + ai * 128 + wr * 64 + m * 16 + fr_e;
;           const float rs = rsqrtf(rsq[ai][m] * (1.f / DM) + 1e-6f);
;           const float c1 = rs * -1.4426950408889634f, rs2 = rs * rs;
;           u16* orow = p.Bbuf + blk_off(row, cpn * 128 + wc * 32, DFF) + wn16;
;           uint2 o2[2];
; #pragma unroll
;           for (int n = 0; n < 2; ++n) {
;             f32x4 g = acc[ai][0][m][n], u = acc[ai][1][m][n];
;             float h[4];
; #pragma unroll
;             for (int j = 0; j < 4; ++j) h[j] = (g[j] * u[j]) * (rs2 * __builtin_amdgcn_rcpf(1.f + __builtin_amdgcn_exp2f(g[j] * c1)));
;             o2[n].x = pk2(h[0], h[1]); o2[n].y = pk2(h[2], h[3]);
;           }
;           *(uint4*)orow = widen_pair(o2[0], o2[1]);
;         }
	v_mul_f32_e32 v61, 0xbfb8aa3b, v60
	v_mul_f32_e32 v68, v61, v56
	v_mul_f32_e32 v69, v61, v57
	v_exp_f32_e32 v68, v68
	v_exp_f32_e32 v69, v69
	v_mul_f32_e32 v70, v61, v58
	v_mul_f32_e32 v71, v61, v59
	v_exp_f32_e32 v70, v70
	v_exp_f32_e32 v71, v71
	v_add_f32_e32 v68, 1.0, v68
	v_add_f32_e32 v69, 1.0, v69
	v_rcp_f32_e32 v68, v68
	v_rcp_f32_e32 v69, v69
	v_pk_mul_f32 v[58:59], v[58:59], v[66:67]
	v_add_f32_e32 v66, 1.0, v70
	v_add_f32_e32 v67, 1.0, v71
	v_rcp_f32_e32 v66, v66
	v_rcp_f32_e32 v67, v67
	v_mul_f32_e32 v60, v60, v60
	v_pk_mul_f32 v[56:57], v[56:57], v[64:65]
	v_pk_mul_f32 v[64:65], v[60:61], v[68:69] op_sel_hi:[0,1]
	v_pk_mul_f32 v[56:57], v[64:65], v[56:57]
	v_pk_mul_f32 v[64:65], v[60:61], v[66:67] op_sel_hi:[0,1]
	v_cvt_pk_bf16_f32 v56, v56, v57
	v_mul_f32_e32 v57, v61, v48
	v_pk_mul_f32 v[58:59], v[64:65], v[58:59]
	v_exp_f32_e32 v64, v57
	v_mul_f32_e32 v57, v61, v49
	v_exp_f32_e32 v65, v57
	v_cvt_pk_bf16_f32 v57, v58, v59
	v_add_f32_e32 v58, 1.0, v64
	v_mul_f32_e32 v64, v61, v50
	v_mul_f32_e32 v61, v61, v51
	v_exp_f32_e32 v64, v64
	v_exp_f32_e32 v61, v61
	v_add_f32_e32 v59, 1.0, v65
	v_rcp_f32_e32 v58, v58
	v_rcp_f32_e32 v59, v59
	v_pk_mul_f32 v[50:51], v[50:51], v[54:55]
	v_add_f32_e32 v54, 1.0, v64
	v_add_f32_e32 v55, 1.0, v61
	v_rcp_f32_e32 v54, v54
	v_rcp_f32_e32 v55, v55
	v_pk_mul_f32 v[48:49], v[48:49], v[52:53]
	v_pk_mul_f32 v[52:53], v[60:61], v[58:59] op_sel_hi:[0,1]
	v_pk_mul_f32 v[48:49], v[52:53], v[48:49]
	v_pk_mul_f32 v[52:53], v[60:61], v[54:55] op_sel_hi:[0,1]
	v_pk_mul_f32 v[50:51], v[52:53], v[50:51]
	s_lshl_b64 s[52:53], s[52:53], 14
	v_cvt_pk_bf16_f32 v59, v50, v51
	v_fmamk_f32 v50, v239, 0x3a000000, v236
	v_mul_f32_e32 v51, 0x4b800000, v50
	v_cmp_gt_f32_e32 vcc, s74, v50
	s_add_u32 s52, s92, s52
	s_addc_u32 s53, s93, s53
	v_cndmask_b32_e32 v50, v50, v51, vcc
	v_rsq_f32_e32 v50, v50
	v_lshl_add_u64 v[62:63], s[52:53], 0, v[214:215]
	v_lshl_add_u64 v[62:63], v[62:63], 0, s[22:23]
	v_cvt_pk_bf16_f32 v58, v48, v49
	v_mul_f32_e32 v51, 0x45800000, v50
	v_cndmask_b32_e32 v50, v50, v51, vcc
	v_mul_f32_e32 v51, 0xbfb8aa3b, v50
	v_mul_f32_e32 v52, v51, v40
	v_mul_f32_e32 v53, v51, v41
	v_exp_f32_e32 v52, v52
	v_exp_f32_e32 v53, v53
	v_mul_f32_e32 v54, v51, v42
	v_mul_f32_e32 v55, v51, v43
	v_exp_f32_e32 v54, v54
	v_exp_f32_e32 v55, v55
	v_add_f32_e32 v52, 1.0, v52
	v_add_f32_e32 v53, 1.0, v53
	v_rcp_f32_e32 v52, v52
	v_rcp_f32_e32 v53, v53
	v_pk_mul_f32 v[42:43], v[42:43], v[46:47]
	v_add_f32_e32 v46, 1.0, v54
	v_add_f32_e32 v47, 1.0, v55
	v_rcp_f32_e32 v46, v46
	v_rcp_f32_e32 v47, v47
	v_mul_f32_e32 v50, v50, v50
	v_pk_mul_f32 v[40:41], v[40:41], v[44:45]
	v_pk_mul_f32 v[44:45], v[50:51], v[52:53] op_sel_hi:[0,1]
	v_pk_mul_f32 v[40:41], v[44:45], v[40:41]
	v_pk_mul_f32 v[44:45], v[50:51], v[46:47] op_sel_hi:[0,1]
	v_cvt_pk_bf16_f32 v40, v40, v41
	v_mul_f32_e32 v41, v51, v32
	v_pk_mul_f32 v[42:43], v[44:45], v[42:43]
	v_exp_f32_e32 v44, v41
	v_mul_f32_e32 v41, v51, v33
	v_exp_f32_e32 v45, v41
	v_cvt_pk_bf16_f32 v41, v42, v43
	v_add_f32_e32 v42, 1.0, v44
	v_rcp_f32_e32 v42, v42
	v_add_f32_e32 v43, 1.0, v45
	v_rcp_f32_e32 v43, v43
	v_pk_mul_f32 v[32:33], v[32:33], v[36:37]
	v_mul_f32_e32 v44, v51, v34
	v_mul_f32_e32 v45, v51, v35
	v_pk_mul_f32 v[36:37], v[50:51], v[42:43] op_sel_hi:[0,1]
	v_pk_mul_f32 v[32:33], v[36:37], v[32:33]
	v_exp_f32_e32 v44, v44
	v_exp_f32_e32 v45, v45
	v_cvt_pk_bf16_f32 v42, v32, v33
	v_fmamk_f32 v32, v238, 0x3a000000, v236
	v_mul_f32_e32 v33, 0x4b800000, v32
	v_cmp_gt_f32_e32 vcc, s74, v32
	v_pk_mul_f32 v[34:35], v[34:35], v[38:39]
	v_add_f32_e32 v38, 1.0, v44
	v_cndmask_b32_e32 v32, v32, v33, vcc
	v_rsq_f32_e32 v32, v32
	v_add_f32_e32 v39, 1.0, v45
	v_rcp_f32_e32 v38, v38
	v_rcp_f32_e32 v39, v39
	v_mul_f32_e32 v33, 0x45800000, v32
	v_cndmask_b32_e32 v32, v32, v33, vcc
	v_mul_f32_e32 v33, 0xbfb8aa3b, v32
	v_pk_mul_f32 v[36:37], v[50:51], v[38:39] op_sel_hi:[0,1]
	v_pk_mul_f32 v[34:35], v[36:37], v[34:35]
	v_mul_f32_e32 v36, v33, v24
	v_mul_f32_e32 v37, v33, v25
	v_exp_f32_e32 v36, v36
	v_exp_f32_e32 v37, v37
	v_mul_f32_e32 v38, v33, v26
	v_mul_f32_e32 v39, v33, v27
	v_exp_f32_e32 v38, v38
	v_exp_f32_e32 v39, v39
; #define SCHED __builtin_amdgcn_sched_barrier(0)
; template <int K, int EPI, bool MIX = false>
; __device__ __forceinline__ void gemm_phase(const Params& p, const u16* __restrict__ A, const u16* __restrict__ Bt,
;                            const float* __restrict__ rs_in, float* __restrict__ ssq_out, float alpha, bool rev = false) {
;     ...
;     if constexpr (EPI == EPI_SWIGLU) {
; #pragma unroll
;       for (int ai = 0; ai < 2; ++ai)
; #pragma unroll
;         for (int m = 0; m < 4; ++m) {
;           int row = brow + ai * 128 + wr * 64 + m * 16 + fr_e;
;           const float rs = rsqrtf(rsq[ai][m] * (1.f / DM) + 1e-6f);
;           const float c1 = rs * -1.4426950408889634f, rs2 = rs * rs;
;           u16* orow = p.Bbuf + blk_off(row, cpn * 128 + wc * 32, DFF) + wn16;
;           uint2 o2[2];
; #pragma unroll
;           for (int n = 0; n < 2; ++n) {
;             f32x4 g = acc[ai][0][m][n], u = acc[ai][1][m][n];
;             float h[4];
; #pragma unroll
;             for (int j = 0; j < 4; ++j) h[j] = (g[j] * u[j]) * (rs2 * __builtin_amdgcn_rcpf(1.f + __builtin_amdgcn_exp2f(g[j] * c1)));
;             o2[n].x = pk2(h[0], h[1]); o2[n].y = pk2(h[2], h[3]);
;           }
;           *(uint4*)orow = widen_pair(o2[0], o2[1]);
;         }
;     ...
;     if (!more) break;
;     asm volatile("" ::: "memory");
;     SCHED;
;   }
	v_add_f32_e32 v36, 1.0, v36
	v_add_f32_e32 v37, 1.0, v37
	v_rcp_f32_e32 v36, v36
	v_rcp_f32_e32 v37, v37
	v_pk_mul_f32 v[26:27], v[26:27], v[30:31]
	v_add_f32_e32 v30, 1.0, v38
	v_add_f32_e32 v31, 1.0, v39
	v_rcp_f32_e32 v30, v30
	v_rcp_f32_e32 v31, v31
	v_mul_f32_e32 v32, v32, v32
	v_pk_mul_f32 v[24:25], v[24:25], v[28:29]
	v_pk_mul_f32 v[28:29], v[32:33], v[36:37] op_sel_hi:[0,1]
	v_pk_mul_f32 v[24:25], v[28:29], v[24:25]
	v_pk_mul_f32 v[28:29], v[32:33], v[30:31] op_sel_hi:[0,1]
	v_cvt_pk_bf16_f32 v24, v24, v25
	v_mul_f32_e32 v25, v33, v16
	v_pk_mul_f32 v[26:27], v[28:29], v[26:27]
	v_exp_f32_e32 v28, v25
	v_mul_f32_e32 v25, v33, v17
	v_exp_f32_e32 v29, v25
	v_cvt_pk_bf16_f32 v25, v26, v27
	v_add_f32_e32 v26, 1.0, v28
	v_mul_f32_e32 v28, v33, v18
	v_add_f32_e32 v27, 1.0, v29
	v_mul_f32_e32 v29, v33, v19
	v_exp_f32_e32 v28, v28
	v_exp_f32_e32 v29, v29
	v_rcp_f32_e32 v26, v26
	v_rcp_f32_e32 v27, v27
	v_pk_mul_f32 v[18:19], v[18:19], v[22:23]
	v_add_f32_e32 v22, 1.0, v28
	v_add_f32_e32 v23, 1.0, v29
	v_rcp_f32_e32 v22, v22
	v_rcp_f32_e32 v23, v23
	v_pk_mul_f32 v[16:17], v[16:17], v[20:21]
	v_pk_mul_f32 v[20:21], v[32:33], v[26:27] op_sel_hi:[0,1]
	v_pk_mul_f32 v[16:17], v[20:21], v[16:17]
	v_pk_mul_f32 v[20:21], v[32:33], v[22:23] op_sel_hi:[0,1]
	v_pk_mul_f32 v[18:19], v[20:21], v[18:19]
	v_cvt_pk_bf16_f32 v43, v34, v35
	v_cvt_pk_bf16_f32 v27, v18, v19
	v_fmamk_f32 v18, v237, 0x3a000000, v236
	v_mul_f32_e32 v19, 0x4b800000, v18
	v_cmp_gt_f32_e32 vcc, s74, v18
	v_lshl_add_u64 v[34:35], s[52:53], 0, v[96:97]
	v_lshl_add_u64 v[34:35], v[34:35], 0, s[22:23]
	v_cndmask_b32_e32 v18, v18, v19, vcc
	v_rsq_f32_e32 v18, v18
	v_cvt_pk_bf16_f32 v26, v16, v17
	v_lshl_add_u64 v[16:17], v[34:35], 0, v[112:113]
	s_nop 0
	v_permlane32_swap_b32_e32 v24, v26
	v_permlane32_swap_b32_e32 v25, v27
	global_store_dwordx4 v[16:17], v[24:27], off
	v_mul_f32_e32 v16, 0x45800000, v18
	v_cndmask_b32_e32 v16, v18, v16, vcc
	v_mul_f32_e32 v17, 0xbfb8aa3b, v16
	v_mul_f32_e32 v20, v17, v8
	v_mul_f32_e32 v21, v17, v9
	v_exp_f32_e32 v20, v20
	v_exp_f32_e32 v21, v21
	v_mul_f32_e32 v22, v17, v10
	v_mul_f32_e32 v23, v17, v11
	v_exp_f32_e32 v22, v22
	v_exp_f32_e32 v23, v23
	v_add_f32_e32 v20, 1.0, v20
	v_add_f32_e32 v21, 1.0, v21
	v_rcp_f32_e32 v20, v20
	v_rcp_f32_e32 v21, v21
	v_pk_mul_f32 v[10:11], v[10:11], v[14:15]
	v_add_f32_e32 v14, 1.0, v22
	v_add_f32_e32 v15, 1.0, v23
	v_rcp_f32_e32 v14, v14
	v_rcp_f32_e32 v15, v15
	v_mul_f32_e32 v16, v16, v16
	v_pk_mul_f32 v[8:9], v[8:9], v[12:13]
	v_pk_mul_f32 v[12:13], v[16:17], v[20:21] op_sel_hi:[0,1]
	v_pk_mul_f32 v[8:9], v[12:13], v[8:9]
	v_pk_mul_f32 v[12:13], v[16:17], v[14:15] op_sel_hi:[0,1]
	v_cvt_pk_bf16_f32 v8, v8, v9
	v_mul_f32_e32 v9, v17, v0
	v_pk_mul_f32 v[10:11], v[12:13], v[10:11]
	v_exp_f32_e32 v12, v9
	v_mul_f32_e32 v9, v17, v1
	v_exp_f32_e32 v13, v9
	v_cvt_pk_bf16_f32 v9, v10, v11
	v_add_f32_e32 v10, 1.0, v12
	v_mul_f32_e32 v12, v17, v2
	v_add_f32_e32 v11, 1.0, v13
	v_mul_f32_e32 v13, v17, v3
	v_exp_f32_e32 v12, v12
	v_exp_f32_e32 v13, v13
	v_rcp_f32_e32 v10, v10
	v_rcp_f32_e32 v11, v11
	v_pk_mul_f32 v[2:3], v[2:3], v[6:7]
	v_add_f32_e32 v6, 1.0, v12
	v_add_f32_e32 v7, 1.0, v13
	v_rcp_f32_e32 v6, v6
	v_rcp_f32_e32 v7, v7
	v_pk_mul_f32 v[0:1], v[0:1], v[4:5]
	v_pk_mul_f32 v[4:5], v[16:17], v[10:11] op_sel_hi:[0,1]
	v_pk_mul_f32 v[0:1], v[4:5], v[0:1]
	v_pk_mul_f32 v[4:5], v[16:17], v[6:7] op_sel_hi:[0,1]
	v_lshl_add_u64 v[18:19], s[52:53], 0, v[80:81]
	v_pk_mul_f32 v[2:3], v[4:5], v[2:3]
	v_lshl_add_u64 v[18:19], v[18:19], 0, s[22:23]
	v_cvt_pk_bf16_f32 v10, v0, v1
	v_cvt_pk_bf16_f32 v11, v2, v3
	v_lshl_add_u64 v[48:49], v[62:63], 0, v[112:113]
	v_permlane32_swap_b32_e32 v56, v58
	v_permlane32_swap_b32_e32 v57, v59
	v_permlane32_swap_b32_e32 v40, v42
	v_permlane32_swap_b32_e32 v41, v43
	v_lshl_add_u64 v[0:1], v[18:19], 0, v[112:113]
	v_permlane32_swap_b32_e32 v8, v10
	v_permlane32_swap_b32_e32 v9, v11
	s_and_b64 vcc, exec, s[4:5]
	s_mov_b64 s[4:5], -1
	global_store_dwordx4 v[48:49], v[56:59], off
	global_store_dwordx4 v[48:49], v[40:43], off offset:2048
	global_store_dwordx4 v[0:1], v[8:11], off
	s_cbranch_vccnz .LBB0_421
	s_mov_b64 s[4:5], 0
	s_branch .LBB0_421

; #define SCHED __builtin_amdgcn_sched_barrier(0)
; template <int K, int EPI, bool MIX = false>
; __device__ __forceinline__ void gemm_phase(const Params& p, const u16* __restrict__ A, const u16* __restrict__ Bt,
;                            const float* __restrict__ rs_in, float* __restrict__ ssq_out, float alpha, bool rev = false) {
;     ...
;   for (;;) {
;     f32x4 acc[2][2][4][2];
; #pragma unroll
;     for (int a = 0; a < 2; ++a)
; #pragma unroll
;       for (int b = 0; b < 2; ++b)
; #pragma unroll
;         for (int m = 0; m < 4; ++m)
; #pragma unroll
;           for (int n = 0; n < 2; ++n) acc[a][b][m][n] = f32x4{0.f, 0.f, 0.f, 0.f};
;     bf16x8 At[4][2], B0[2][2], B1[2][2];
;     asm volatile("" ::: "memory");
;     SCHED;
.LBB0_461:
	s_andn2_b64 vcc, exec, s[2:3]
	s_cbranch_vccz .LBB0_502
	s_and_b64 vcc, exec, s[22:23]
	s_cbranch_vccnz .Llate_p7_done
	s_barrier
.Llate_p7_done:
.LBB0_462:
	s_mov_b32 s70, s68
	s_mov_b32 s69, s67
	v_mov_b32_e32 v0, 0
	s_mov_b32 s67, -2
	s_mov_b64 s[2:3], s[10:11]
	s_mov_b64 s[50:51], s[4:5]
	s_mov_b64 s[52:53], s[8:9]
	s_waitcnt lgkmcnt(0)
	v_mov_b32_e32 v1, v0
	v_mov_b32_e32 v2, v0
	v_mov_b32_e32 v3, v0
	v_mov_b32_e32 v4, v0
	v_mov_b32_e32 v5, v0
	v_mov_b32_e32 v6, v0
	v_mov_b32_e32 v7, v0
	v_mov_b32_e32 v8, v0
	v_mov_b32_e32 v9, v0
	v_mov_b32_e32 v10, v0
	v_mov_b32_e32 v11, v0
	v_mov_b32_e32 v12, v0
	v_mov_b32_e32 v13, v0
	v_mov_b32_e32 v14, v0
	v_mov_b32_e32 v15, v0
	v_mov_b32_e32 v16, v0
	v_mov_b32_e32 v17, v0
	v_mov_b32_e32 v18, v0
	v_mov_b32_e32 v19, v0
	v_mov_b32_e32 v20, v0
	v_mov_b32_e32 v21, v0
	v_mov_b32_e32 v22, v0
	v_mov_b32_e32 v23, v0
	v_mov_b32_e32 v24, v0
	v_mov_b32_e32 v25, v0
	v_mov_b32_e32 v26, v0
	v_mov_b32_e32 v27, v0
	v_mov_b32_e32 v28, v0
	v_mov_b32_e32 v29, v0
	v_mov_b32_e32 v30, v0
	v_mov_b32_e32 v31, v0
	v_mov_b32_e32 v32, v0
	v_mov_b32_e32 v33, v0
	v_mov_b32_e32 v34, v0
	v_mov_b32_e32 v35, v0
	v_mov_b32_e32 v36, v0
	v_mov_b32_e32 v37, v0
	v_mov_b32_e32 v38, v0
	v_mov_b32_e32 v39, v0
	v_mov_b32_e32 v40, v0
	v_mov_b32_e32 v41, v0
	v_mov_b32_e32 v42, v0
	v_mov_b32_e32 v43, v0
	v_mov_b32_e32 v44, v0
	v_mov_b32_e32 v45, v0
	v_mov_b32_e32 v46, v0
	v_mov_b32_e32 v47, v0
	v_mov_b32_e32 v48, v0
	v_mov_b32_e32 v49, v0
	v_mov_b32_e32 v50, v0
	v_mov_b32_e32 v51, v0
	v_mov_b32_e32 v52, v0
	v_mov_b32_e32 v53, v0
	v_mov_b32_e32 v54, v0
	v_mov_b32_e32 v55, v0
	v_mov_b32_e32 v56, v0
	v_mov_b32_e32 v57, v0
	v_mov_b32_e32 v58, v0
	v_mov_b32_e32 v59, v0
	v_mov_b32_e32 v60, v0
	v_mov_b32_e32 v61, v0
	v_mov_b32_e32 v62, v0
	v_mov_b32_e32 v63, v0
	v_mov_b32_e32 v64, v0
	v_mov_b32_e32 v65, v0
	v_mov_b32_e32 v66, v0
	v_mov_b32_e32 v67, v0
	v_mov_b32_e32 v68, v0
	v_mov_b32_e32 v69, v0
	v_mov_b32_e32 v70, v0
	v_mov_b32_e32 v71, v0
	v_mov_b32_e32 v72, v0
	v_mov_b32_e32 v73, v0
	v_mov_b32_e32 v74, v0
	v_mov_b32_e32 v75, v0
	v_mov_b32_e32 v76, v0
	v_mov_b32_e32 v77, v0
	v_mov_b32_e32 v78, v0
	v_mov_b32_e32 v79, v0
	v_mov_b32_e32 v80, v0
	v_mov_b32_e32 v81, v0
	v_mov_b32_e32 v82, v0
	v_mov_b32_e32 v83, v0
	v_mov_b32_e32 v84, v0
	v_mov_b32_e32 v85, v0
	v_mov_b32_e32 v86, v0
	v_mov_b32_e32 v87, v0
	v_mov_b32_e32 v88, v0
	v_mov_b32_e32 v89, v0
	v_mov_b32_e32 v90, v0
	v_mov_b32_e32 v91, v0
	v_mov_b32_e32 v92, v0
	v_mov_b32_e32 v93, v0
	v_mov_b32_e32 v94, v0
	v_mov_b32_e32 v95, v0
	v_mov_b32_e32 v96, v0
	v_mov_b32_e32 v97, v0
	v_mov_b32_e32 v98, v0
	v_mov_b32_e32 v99, v0
	v_mov_b32_e32 v100, v0
	v_mov_b32_e32 v101, v0
	v_mov_b32_e32 v102, v0
	v_mov_b32_e32 v103, v0
	v_mov_b32_e32 v104, v0
	v_mov_b32_e32 v105, v0
	v_mov_b32_e32 v106, v0
	v_mov_b32_e32 v107, v0
	v_mov_b32_e32 v108, v0
	v_mov_b32_e32 v109, v0
	v_mov_b32_e32 v110, v0
	v_mov_b32_e32 v111, v0
	v_mov_b32_e32 v112, v0
	v_mov_b32_e32 v113, v0
	v_mov_b32_e32 v114, v0
	v_mov_b32_e32 v115, v0
	v_mov_b32_e32 v116, v0
	v_mov_b32_e32 v117, v0
	v_mov_b32_e32 v118, v0
	v_mov_b32_e32 v119, v0
	v_mov_b32_e32 v120, v0
	v_mov_b32_e32 v121, v0
	v_mov_b32_e32 v122, v0
	v_mov_b32_e32 v123, v0
	v_mov_b32_e32 v124, v0
	v_mov_b32_e32 v125, v0
	v_mov_b32_e32 v126, v0
	v_mov_b32_e32 v127, v0

; #define MMA(ai,bj,Af,Bf) do{__builtin_amdgcn_s_setprio(1); \
;     _Pragma("unroll") for(int m=0;m<4;++m) _Pragma("unroll") for(int n=0;n<2;++n) _Pragma("unroll") for(int k=0;k<2;++k) \
;       acc[ai][bj][m][n]=__builtin_amdgcn_mfma_f32_16x16x32_bf16(Bf[n][k],Af[m][k],acc[ai][bj][m][n],0,0,0); \
;     __builtin_amdgcn_s_setprio(0);}while(0)
; #define WAIT_V(n) asm volatile("s_waitcnt vmcnt(" #n ")":::"memory")
; #define BAR __builtin_amdgcn_s_barrier()
; #define STAGE_B(b,h,kt) do{ unsigned char* _d = SB(b,h) + wbase; \
;     if constexpr (BLK) { const char* _s = ((h)?baseB1:baseB0) + (size_t)(kt) * 16384; GLDS(_s + voa, _d); GLDS(_s + 8192 + voa, _d + 8192); } \
;     else { const char* _s = ((h)?baseB1:baseB0) + (kt)*128; GLDS(_s + voa, _d); GLDS(_s + (size_t)128*K + voa, _d + 8192); } }while(0)
; template <int K, int EPI, bool MIX = false>
; __device__ __forceinline__ void gemm_phase(const Params& p, const u16* __restrict__ A, const u16* __restrict__ Bt,
;                            const float* __restrict__ rs_in, float* __restrict__ ssq_out, float alpha, bool rev = false) {
;     ...
;       if (more) { STAGE_B(1,1,1); WAIT_V(6); }
;       BAR; MMA(1,1,At,B1); BAR;
;       if (!more && wr == 0) BAR;
.LBB0_482:
	s_barrier
	s_setprio 1
	v_mfma_f32_16x16x32_bf16 v[24:27], v[132:135], v[208:211], v[24:27]
	v_mfma_f32_16x16x32_bf16 v[56:59], v[136:139], v[212:215], v[24:27]
	v_mfma_f32_16x16x32_bf16 v[24:27], v[128:131], v[172:175], v[152:155]
	v_mfma_f32_16x16x32_bf16 v[44:47], v[140:143], v[200:203], v[24:27]
	v_mfma_f32_16x16x32_bf16 v[24:27], v[132:135], v[172:175], v[156:159]
	v_mfma_f32_16x16x32_bf16 v[8:11], v[132:135], v[168:171], v[8:11]
	v_mfma_f32_16x16x32_bf16 v[28:31], v[128:131], v[208:211], v[28:31]
	v_mfma_f32_16x16x32_bf16 v[40:43], v[136:139], v[200:203], v[24:27]
	v_mfma_f32_16x16x32_bf16 v[12:15], v[128:131], v[168:171], v[12:15]
	v_mfma_f32_16x16x32_bf16 v[24:27], v[136:139], v[204:207], v[8:11]
	v_mfma_f32_16x16x32_bf16 v[8:11], v[128:131], v[160:163], v[184:187]
	v_mfma_f32_16x16x32_bf16 v[60:63], v[140:143], v[212:215], v[28:31]
	v_mfma_f32_16x16x32_bf16 v[28:31], v[140:143], v[204:207], v[12:15]
	v_mfma_f32_16x16x32_bf16 v[12:15], v[140:143], v[164:167], v[8:11]
	v_mfma_f32_16x16x32_bf16 v[8:11], v[132:135], v[160:163], v[188:191]
	v_mfma_f32_16x16x32_bf16 v[8:11], v[136:139], v[164:167], v[8:11]
	s_setprio 0
	s_or_b64 vcc, s[2:3], s[22:23]
	s_cbranch_scc0 .Llate_p7_defer
	s_barrier
.Llate_p7_defer:
	s_andn2_b64 vcc, exec, s[50:51]
	s_cbranch_vccnz .LBB0_484
	s_barrier
